# redundant lgkmcnt(0) after each GEMM compute-segment barrier removed (20 sites)
# baseline (speedup 1.0000x reference)
; #define PG8_STAGE(bufoff, gbase, voff) do { _Pragma("unroll") for (int _i = 0; _i < 2; ++_i) \
;         __builtin_amdgcn_global_load_lds((const unsigned*)((const char*)(gbase) + (voff)[_i]), (PG8_LAS unsigned*)(lds + (bufoff) + ldsw + _i * 8192), 16, 0, 0); } while (0)
; #define PG8_LDA(dst, b, h) do { _Pragma("unroll") for (int m = 0; m < 4; ++m) _Pragma("unroll") for (int k = 0; k < 2; ++k) dst[m][k] = *(const PG8_LAS bf16x8*)(lds + PG8_SA(b, h) + aoff + m * 2048 + k * 1024); } while (0)
; #define PG8_LDB(dst, b, h) do { _Pragma("unroll") for (int n = 0; n < 2; ++n) _Pragma("unroll") for (int k = 0; k < 2; ++k) dst[n][k] = *(const PG8_LAS bf16x8*)(lds + PG8_SB(b, h) + boff + n * 2048 + k * 1024); } while (0)
; #define PG8_WAIT_V(n) asm volatile("s_waitcnt vmcnt(" #n ")" ::: "memory")
; #define PG8_WAIT_L(n) asm volatile("s_waitcnt lgkmcnt(" #n ")" ::: "memory")
; #define PG8_BAR __builtin_amdgcn_s_barrier()
; #define PG8_SCHED __builtin_amdgcn_sched_barrier(0)
; template <class Epi, class Sched, bool ALIGN_EPI = false, bool SP2 = false, bool SPLITK = false>
; __device__ __forceinline__ void gemm_phase(PG8_LAS unsigned char* lds, const Gemm g, const Sched& S, const Epi& E) {
;     ...
;         const char* nA = has_next ? (const char*)g.A + (size_t)nxt.pm * tstep : cA; const char* nB = has_next ? (const char*)g.Bt + (size_t)nxt.pn * tstep : cB;
;         for (int t = 0; t < nt; t += 2) {
;             const bool last = (t == nt - 2);
;             if constexpr (SPLITK) { if (t == nt1) E.mid(acc, cur, wr, wc, fr, fq); }
;             const char* a1 = PG8_TA(t + 1);
;             const char* a2 = last ? nA : PG8_TA(t + 2); const char* b2 = last ? nB : PG8_TB(t + 2);
;             const char* a3 = a2 + kstep; const char* b3 = b2 + kstep;
;             if (last && has_next) S.a_ready(nxt);
;             if constexpr (SP2) {
;             PG8_LDB(B0, 0, 0); PG8_LDB(B1, 0, 1); PG8_SCHED; PG8_LDA(At, 0, 0); PG8_STAGE(PG8_SA(1, 1), a1 + hstep, voffA);
;             PG8_WAIT_V(8); PG8_WAIT_L(0); PG8_BAR; PG8_MMA(0, 0, At, B0); PG8_MMA(0, 1, At, B1); PG8_BAR; PG8_SCHED;
;             PG8_LDA(At, 0, 1); PG8_STAGE(PG8_SB(0, 0), b2, voffB); PG8_STAGE(PG8_SB(0, 1), b2 + hstep, voffB); PG8_STAGE(PG8_SA(0, 0), a2, voffA);
;             PG8_WAIT_V(8); PG8_WAIT_L(0); PG8_BAR; PG8_MMA(1, 0, At, B0); PG8_MMA(1, 1, At, B1); PG8_BAR; PG8_SCHED;
.LBB0_165:
	s_add_u32 s35, s54, 0xfffc0080
	s_addc_u32 s43, s55, -1
	s_add_i32 s45, 0, 0x10000
	s_cmp_eq_u32 s25, 12
	s_cselect_b32 s49, s4, s43
	s_cselect_b32 s48, s12, s35
	s_cselect_b32 s47, s21, s24
	s_cselect_b32 s46, s22, s23
	s_add_i32 s35, 0, 0x14000
	v_add_u32_e32 v142, s45, v198
	v_add_u32_e32 v158, s35, v198
	ds_read_b128 v[130:133], v142
	ds_read_b128 v[134:137], v142 offset:1024
	ds_read_b128 v[138:141], v142 offset:2048
	ds_read_b128 v[142:145], v142 offset:3072
	ds_read_b128 v[146:149], v158
	ds_read_b128 v[150:153], v158 offset:1024
	ds_read_b128 v[154:157], v158 offset:2048
	ds_read_b128 v[158:161], v158 offset:3072
	s_add_i32 m0, s51, 0xc000
	ds_read_b128 v[162:165], v199
	ds_read_b128 v[178:181], v199 offset:1024
	ds_read_b128 v[182:185], v199 offset:2048
	ds_read_b128 v[186:189], v199 offset:3072
	ds_read_b128 v[190:193], v199 offset:4096
	ds_read_b128 v[200:203], v199 offset:5120
	ds_read_b128 v[204:207], v199 offset:6144
	ds_read_b128 v[208:211], v199 offset:7168
	global_load_lds_dwordx4 v174, s[54:55]
	s_add_i32 m0, s51, 0xe000
	s_nop 0
	global_load_lds_dwordx4 v176, s[54:55]
	s_waitcnt vmcnt(8)
	s_waitcnt lgkmcnt(0)
	s_barrier
	s_setprio 1
	v_mfma_f32_16x16x32_bf16 v[126:129], v[130:133], v[162:165], v[126:129]
	v_mfma_f32_16x16x32_bf16 v[122:125], v[138:141], v[162:165], v[122:125]
	v_mfma_f32_16x16x32_bf16 v[114:117], v[130:133], v[182:185], v[114:117]
	v_mfma_f32_16x16x32_bf16 v[106:109], v[138:141], v[182:185], v[106:109]
	v_mfma_f32_16x16x32_bf16 v[98:101], v[130:133], v[190:193], v[98:101]
	v_mfma_f32_16x16x32_bf16 v[90:93], v[138:141], v[190:193], v[90:93]
	v_mfma_f32_16x16x32_bf16 v[82:85], v[130:133], v[204:207], v[82:85]
	v_mfma_f32_16x16x32_bf16 v[74:77], v[138:141], v[204:207], v[74:77]
	v_mfma_f32_16x16x32_bf16 v[126:129], v[134:137], v[178:181], v[126:129]
	v_mfma_f32_16x16x32_bf16 v[122:125], v[142:145], v[178:181], v[122:125]
	v_mfma_f32_16x16x32_bf16 v[114:117], v[134:137], v[186:189], v[114:117]
	v_mfma_f32_16x16x32_bf16 v[106:109], v[142:145], v[186:189], v[106:109]
	v_mfma_f32_16x16x32_bf16 v[98:101], v[134:137], v[200:203], v[98:101]
	v_mfma_f32_16x16x32_bf16 v[90:93], v[142:145], v[200:203], v[90:93]
	v_mfma_f32_16x16x32_bf16 v[82:85], v[134:137], v[208:211], v[82:85]
	v_mfma_f32_16x16x32_bf16 v[74:77], v[142:145], v[208:211], v[74:77]
	v_mfma_f32_16x16x32_bf16 v[118:121], v[146:149], v[162:165], v[118:121]
	v_mfma_f32_16x16x32_bf16 v[110:113], v[154:157], v[162:165], v[110:113]
	v_mfma_f32_16x16x32_bf16 v[102:105], v[146:149], v[182:185], v[102:105]
	v_mfma_f32_16x16x32_bf16 v[94:97], v[154:157], v[182:185], v[94:97]
	v_mfma_f32_16x16x32_bf16 v[86:89], v[146:149], v[190:193], v[86:89]
	v_mfma_f32_16x16x32_bf16 v[78:81], v[154:157], v[190:193], v[78:81]
	v_mfma_f32_16x16x32_bf16 v[70:73], v[146:149], v[204:207], v[70:73]
	v_mfma_f32_16x16x32_bf16 v[66:69], v[154:157], v[204:207], v[66:69]
	v_mfma_f32_16x16x32_bf16 v[118:121], v[150:153], v[178:181], v[118:121]
	v_mfma_f32_16x16x32_bf16 v[110:113], v[158:161], v[178:181], v[110:113]
	v_mfma_f32_16x16x32_bf16 v[102:105], v[150:153], v[186:189], v[102:105]
	v_mfma_f32_16x16x32_bf16 v[94:97], v[158:161], v[186:189], v[94:97]
	v_mfma_f32_16x16x32_bf16 v[86:89], v[150:153], v[200:203], v[86:89]
	v_mfma_f32_16x16x32_bf16 v[78:81], v[158:161], v[200:203], v[78:81]
	v_mfma_f32_16x16x32_bf16 v[70:73], v[150:153], v[208:211], v[70:73]
	v_mfma_f32_16x16x32_bf16 v[66:69], v[158:161], v[208:211], v[66:69]
	s_setprio 0
	s_barrier
	s_add_i32 s43, s45, s33
	s_mov_b32 m0, s43
	ds_read_b128 v[162:165], v199 offset:16384
	ds_read_b128 v[178:181], v199 offset:17408
	ds_read_b128 v[182:185], v199 offset:18432
	ds_read_b128 v[186:189], v199 offset:19456
	ds_read_b128 v[190:193], v199 offset:20480
	ds_read_b128 v[200:203], v199 offset:21504
	ds_read_b128 v[204:207], v199 offset:22528
	ds_read_b128 v[208:211], v199 offset:23552
	global_load_lds_dwordx4 v0, s[46:47]
	s_add_i32 m0, s43, 0x2000
	s_add_u32 s76, s46, 0x40000
	s_addc_u32 s77, s47, 0
	s_add_i32 s35, s35, s33
	global_load_lds_dwordx4 v172, s[46:47]
	s_mov_b32 m0, s35
	s_nop 0
	global_load_lds_dwordx4 v0, s[76:77]
	s_add_i32 m0, s35, 0x2000
	s_nop 0
	global_load_lds_dwordx4 v172, s[76:77]
	s_mov_b32 m0, s51
	s_nop 0
	global_load_lds_dwordx4 v168, s[48:49]
	s_mov_b32 m0, s53
	s_nop 0
	global_load_lds_dwordx4 v170, s[48:49]
	s_waitcnt vmcnt(8)
	s_waitcnt lgkmcnt(0)
	s_barrier
	s_setprio 1
	v_mfma_f32_16x16x32_bf16 v[62:65], v[130:133], v[162:165], v[62:65]
	v_mfma_f32_16x16x32_bf16 v[58:61], v[138:141], v[162:165], v[58:61]
	v_mfma_f32_16x16x32_bf16 v[50:53], v[130:133], v[182:185], v[50:53]
	v_mfma_f32_16x16x32_bf16 v[42:45], v[138:141], v[182:185], v[42:45]
	v_mfma_f32_16x16x32_bf16 v[34:37], v[130:133], v[190:193], v[34:37]
	v_mfma_f32_16x16x32_bf16 v[26:29], v[138:141], v[190:193], v[26:29]
	v_mfma_f32_16x16x32_bf16 v[18:21], v[130:133], v[204:207], v[18:21]
	v_mfma_f32_16x16x32_bf16 v[10:13], v[138:141], v[204:207], v[10:13]
	v_mfma_f32_16x16x32_bf16 v[62:65], v[134:137], v[178:181], v[62:65]
	v_mfma_f32_16x16x32_bf16 v[58:61], v[142:145], v[178:181], v[58:61]
	v_mfma_f32_16x16x32_bf16 v[50:53], v[134:137], v[186:189], v[50:53]
	v_mfma_f32_16x16x32_bf16 v[42:45], v[142:145], v[186:189], v[42:45]
	v_mfma_f32_16x16x32_bf16 v[34:37], v[134:137], v[200:203], v[34:37]
	v_mfma_f32_16x16x32_bf16 v[26:29], v[142:145], v[200:203], v[26:29]
	v_mfma_f32_16x16x32_bf16 v[18:21], v[134:137], v[208:211], v[18:21]
	v_mfma_f32_16x16x32_bf16 v[10:13], v[142:145], v[208:211], v[10:13]
	v_mfma_f32_16x16x32_bf16 v[54:57], v[146:149], v[162:165], v[54:57]
	v_mfma_f32_16x16x32_bf16 v[46:49], v[154:157], v[162:165], v[46:49]
	v_mfma_f32_16x16x32_bf16 v[38:41], v[146:149], v[182:185], v[38:41]
	v_mfma_f32_16x16x32_bf16 v[30:33], v[154:157], v[182:185], v[30:33]
	v_mfma_f32_16x16x32_bf16 v[22:25], v[146:149], v[190:193], v[22:25]
	v_mfma_f32_16x16x32_bf16 v[14:17], v[154:157], v[190:193], v[14:17]
	v_mfma_f32_16x16x32_bf16 v[6:9], v[146:149], v[204:207], v[6:9]
	v_mfma_f32_16x16x32_bf16 v[2:5], v[154:157], v[204:207], v[2:5]
	v_mfma_f32_16x16x32_bf16 v[54:57], v[150:153], v[178:181], v[54:57]
	v_mfma_f32_16x16x32_bf16 v[46:49], v[158:161], v[178:181], v[46:49]
	v_mfma_f32_16x16x32_bf16 v[38:41], v[150:153], v[186:189], v[38:41]
	v_mfma_f32_16x16x32_bf16 v[30:33], v[158:161], v[186:189], v[30:33]
	v_mfma_f32_16x16x32_bf16 v[22:25], v[150:153], v[200:203], v[22:25]
	v_mfma_f32_16x16x32_bf16 v[14:17], v[158:161], v[200:203], v[14:17]
	v_mfma_f32_16x16x32_bf16 v[6:9], v[150:153], v[208:211], v[6:9]
	v_mfma_f32_16x16x32_bf16 v[2:5], v[158:161], v[208:211], v[2:5]
	s_setprio 0
	s_barrier
; #define PG8_STAGE(bufoff, gbase, voff) do { _Pragma("unroll") for (int _i = 0; _i < 2; ++_i) \
;         __builtin_amdgcn_global_load_lds((const unsigned*)((const char*)(gbase) + (voff)[_i]), (PG8_LAS unsigned*)(lds + (bufoff) + ldsw + _i * 8192), 16, 0, 0); } while (0)
; #define PG8_LDA(dst, b, h) do { _Pragma("unroll") for (int m = 0; m < 4; ++m) _Pragma("unroll") for (int k = 0; k < 2; ++k) dst[m][k] = *(const PG8_LAS bf16x8*)(lds + PG8_SA(b, h) + aoff + m * 2048 + k * 1024); } while (0)
; #define PG8_LDB(dst, b, h) do { _Pragma("unroll") for (int n = 0; n < 2; ++n) _Pragma("unroll") for (int k = 0; k < 2; ++k) dst[n][k] = *(const PG8_LAS bf16x8*)(lds + PG8_SB(b, h) + boff + n * 2048 + k * 1024); } while (0)
; #define PG8_MMA(ai, bj, At, Bt) do { __builtin_amdgcn_s_setprio(1); _Pragma("unroll") for (int m = 0; m < 4; ++m) _Pragma("unroll") for (int n = 0; n < 2; ++n) _Pragma("unroll") for (int k = 0; k < 2; ++k) \
;         acc[ai][bj][m][n] = __builtin_amdgcn_mfma_f32_16x16x32_bf16(Bt[n][k], At[m][k], acc[ai][bj][m][n], 0, 0, 0); __builtin_amdgcn_s_setprio(0); } while (0)
; #define PG8_WAIT_V(n) asm volatile("s_waitcnt vmcnt(" #n ")" ::: "memory")
; #define PG8_WAIT_L(n) asm volatile("s_waitcnt lgkmcnt(" #n ")" ::: "memory")
; #define PG8_BAR __builtin_amdgcn_s_barrier()
; #define PG8_SCHED __builtin_amdgcn_sched_barrier(0)
; template <class Epi, class Sched, bool ALIGN_EPI = false, bool SP2 = false, bool SPLITK = false>
; __device__ __forceinline__ void gemm_phase(PG8_LAS unsigned char* lds, const Gemm g, const Sched& S, const Epi& E) {
;     ...
;             PG8_LDB(B0, 1, 0); PG8_LDB(B1, 1, 1); PG8_SCHED; PG8_LDA(At, 1, 0); PG8_STAGE(PG8_SA(0, 1), a2 + hstep, voffA);
;             PG8_WAIT_V(8); PG8_WAIT_L(0); PG8_BAR; PG8_MMA(0, 0, At, B0); PG8_MMA(0, 1, At, B1); PG8_BAR; PG8_SCHED;
;             PG8_LDA(At, 1, 1); PG8_STAGE(PG8_SB(1, 0), b3, voffB); PG8_STAGE(PG8_SB(1, 1), b3 + hstep, voffB); PG8_STAGE(PG8_SA(1, 0), a3, voffA);
;             PG8_WAIT_V(8); PG8_WAIT_L(0); PG8_BAR; PG8_MMA(1, 0, At, B0); PG8_MMA(1, 1, At, B1); PG8_BAR; PG8_SCHED;
;     ...
;         if constexpr (ALIGN_EPI) { if (wr == 0) PG8_BAR; }
	s_add_i32 s35, 0, 0x18000
	s_add_i32 s43, 0, 0x1c000
	v_add_u32_e32 v142, s35, v198
	v_add_u32_e32 v158, s43, v198
	ds_read_b128 v[130:133], v142
	ds_read_b128 v[134:137], v142 offset:1024
	ds_read_b128 v[138:141], v142 offset:2048
	ds_read_b128 v[142:145], v142 offset:3072
	ds_read_b128 v[146:149], v158
	ds_read_b128 v[150:153], v158 offset:1024
	ds_read_b128 v[154:157], v158 offset:2048
	ds_read_b128 v[158:161], v158 offset:3072
	s_add_u32 s48, s48, 0x40000
	s_addc_u32 s49, s49, 0
	s_mov_b32 m0, s56
	ds_read_b128 v[162:165], v199 offset:32768
	ds_read_b128 v[178:181], v199 offset:33792
	ds_read_b128 v[182:185], v199 offset:34816
	ds_read_b128 v[186:189], v199 offset:35840
	ds_read_b128 v[190:193], v199 offset:36864
	ds_read_b128 v[200:203], v199 offset:37888
	ds_read_b128 v[204:207], v199 offset:38912
	ds_read_b128 v[208:211], v199 offset:39936
	global_load_lds_dwordx4 v168, s[48:49]
	s_mov_b32 m0, s57
	s_nop 0
	global_load_lds_dwordx4 v170, s[48:49]
	s_waitcnt vmcnt(8)
	s_waitcnt lgkmcnt(0)
	s_barrier
	s_setprio 1
	v_mfma_f32_16x16x32_bf16 v[126:129], v[130:133], v[162:165], v[126:129]
	v_mfma_f32_16x16x32_bf16 v[122:125], v[138:141], v[162:165], v[122:125]
	v_mfma_f32_16x16x32_bf16 v[114:117], v[130:133], v[182:185], v[114:117]
	v_mfma_f32_16x16x32_bf16 v[106:109], v[138:141], v[182:185], v[106:109]
	v_mfma_f32_16x16x32_bf16 v[98:101], v[130:133], v[190:193], v[98:101]
	v_mfma_f32_16x16x32_bf16 v[90:93], v[138:141], v[190:193], v[90:93]
	v_mfma_f32_16x16x32_bf16 v[82:85], v[130:133], v[204:207], v[82:85]
	v_mfma_f32_16x16x32_bf16 v[74:77], v[138:141], v[204:207], v[74:77]
	v_mfma_f32_16x16x32_bf16 v[126:129], v[134:137], v[178:181], v[126:129]
	v_mfma_f32_16x16x32_bf16 v[122:125], v[142:145], v[178:181], v[122:125]
	v_mfma_f32_16x16x32_bf16 v[114:117], v[134:137], v[186:189], v[114:117]
	v_mfma_f32_16x16x32_bf16 v[106:109], v[142:145], v[186:189], v[106:109]
	v_mfma_f32_16x16x32_bf16 v[98:101], v[134:137], v[200:203], v[98:101]
	v_mfma_f32_16x16x32_bf16 v[90:93], v[142:145], v[200:203], v[90:93]
	v_mfma_f32_16x16x32_bf16 v[82:85], v[134:137], v[208:211], v[82:85]
	v_mfma_f32_16x16x32_bf16 v[74:77], v[142:145], v[208:211], v[74:77]
	v_mfma_f32_16x16x32_bf16 v[118:121], v[146:149], v[162:165], v[118:121]
	v_mfma_f32_16x16x32_bf16 v[110:113], v[154:157], v[162:165], v[110:113]
	v_mfma_f32_16x16x32_bf16 v[102:105], v[146:149], v[182:185], v[102:105]
	v_mfma_f32_16x16x32_bf16 v[94:97], v[154:157], v[182:185], v[94:97]
	v_mfma_f32_16x16x32_bf16 v[86:89], v[146:149], v[190:193], v[86:89]
	v_mfma_f32_16x16x32_bf16 v[78:81], v[154:157], v[190:193], v[78:81]
	v_mfma_f32_16x16x32_bf16 v[70:73], v[146:149], v[204:207], v[70:73]
	v_mfma_f32_16x16x32_bf16 v[66:69], v[154:157], v[204:207], v[66:69]
	v_mfma_f32_16x16x32_bf16 v[118:121], v[150:153], v[178:181], v[118:121]
	v_mfma_f32_16x16x32_bf16 v[110:113], v[158:161], v[178:181], v[110:113]
	v_mfma_f32_16x16x32_bf16 v[102:105], v[150:153], v[186:189], v[102:105]
	v_mfma_f32_16x16x32_bf16 v[94:97], v[158:161], v[186:189], v[94:97]
	v_mfma_f32_16x16x32_bf16 v[86:89], v[150:153], v[200:203], v[86:89]
	v_mfma_f32_16x16x32_bf16 v[78:81], v[158:161], v[200:203], v[78:81]
	v_mfma_f32_16x16x32_bf16 v[70:73], v[150:153], v[208:211], v[70:73]
	v_mfma_f32_16x16x32_bf16 v[66:69], v[158:161], v[208:211], v[66:69]
	s_setprio 0
	s_barrier
	s_add_i32 s35, s35, s33
	s_add_u32 s46, s46, 0x80
	s_addc_u32 s47, s47, 0
	s_mov_b32 m0, s35
	ds_read_b128 v[162:165], v199 offset:49152
	ds_read_b128 v[178:181], v199 offset:50176
	ds_read_b128 v[182:185], v199 offset:51200
	ds_read_b128 v[186:189], v199 offset:52224
	ds_read_b128 v[190:193], v199 offset:53248
	ds_read_b128 v[200:203], v199 offset:54272
	ds_read_b128 v[204:207], v199 offset:55296
	ds_read_b128 v[208:211], v199 offset:56320
	global_load_lds_dwordx4 v0, s[46:47]
	s_add_i32 m0, s35, 0x2000
	s_add_i32 s35, s43, s33
	global_load_lds_dwordx4 v172, s[46:47]
	s_add_u32 s46, s46, 0x40000
	s_addc_u32 s47, s47, 0
	s_mov_b32 m0, s35
	s_nop 0
	global_load_lds_dwordx4 v0, s[46:47]
	s_add_i32 m0, s35, 0x2000
	s_nop 0
	global_load_lds_dwordx4 v172, s[46:47]
	s_sub_u32 s76, s48, 0x3ff80
	s_subb_u32 s77, s49, 0
	s_mov_b32 m0, s58
	s_nop 0
	global_load_lds_dwordx4 v168, s[76:77]
	s_mov_b32 m0, s59
	s_nop 0
	global_load_lds_dwordx4 v170, s[76:77]
	s_waitcnt vmcnt(8)
	s_waitcnt lgkmcnt(0)
	s_barrier
	s_setprio 1
	v_mfma_f32_16x16x32_bf16 v[62:65], v[130:133], v[162:165], v[62:65]
	v_mfma_f32_16x16x32_bf16 v[58:61], v[138:141], v[162:165], v[58:61]
	v_mfma_f32_16x16x32_bf16 v[50:53], v[130:133], v[182:185], v[50:53]
	v_mfma_f32_16x16x32_bf16 v[42:45], v[138:141], v[182:185], v[42:45]
	v_mfma_f32_16x16x32_bf16 v[34:37], v[130:133], v[190:193], v[34:37]
	v_mfma_f32_16x16x32_bf16 v[26:29], v[138:141], v[190:193], v[26:29]
	v_mfma_f32_16x16x32_bf16 v[18:21], v[130:133], v[204:207], v[18:21]
	v_mfma_f32_16x16x32_bf16 v[10:13], v[138:141], v[204:207], v[10:13]
	v_mfma_f32_16x16x32_bf16 v[62:65], v[134:137], v[178:181], v[62:65]
	v_mfma_f32_16x16x32_bf16 v[58:61], v[142:145], v[178:181], v[58:61]
	v_mfma_f32_16x16x32_bf16 v[50:53], v[134:137], v[186:189], v[50:53]
	v_mfma_f32_16x16x32_bf16 v[42:45], v[142:145], v[186:189], v[42:45]
	v_mfma_f32_16x16x32_bf16 v[34:37], v[134:137], v[200:203], v[34:37]
	v_mfma_f32_16x16x32_bf16 v[26:29], v[142:145], v[200:203], v[26:29]
	v_mfma_f32_16x16x32_bf16 v[18:21], v[134:137], v[208:211], v[18:21]
	v_mfma_f32_16x16x32_bf16 v[10:13], v[142:145], v[208:211], v[10:13]
	v_mfma_f32_16x16x32_bf16 v[54:57], v[146:149], v[162:165], v[54:57]
	v_mfma_f32_16x16x32_bf16 v[46:49], v[154:157], v[162:165], v[46:49]
	v_mfma_f32_16x16x32_bf16 v[38:41], v[146:149], v[182:185], v[38:41]
	v_mfma_f32_16x16x32_bf16 v[30:33], v[154:157], v[182:185], v[30:33]
	v_mfma_f32_16x16x32_bf16 v[22:25], v[146:149], v[190:193], v[22:25]
	v_mfma_f32_16x16x32_bf16 v[14:17], v[154:157], v[190:193], v[14:17]
	v_mfma_f32_16x16x32_bf16 v[6:9], v[146:149], v[204:207], v[6:9]
	v_mfma_f32_16x16x32_bf16 v[2:5], v[154:157], v[204:207], v[2:5]
	v_mfma_f32_16x16x32_bf16 v[54:57], v[150:153], v[178:181], v[54:57]
	v_mfma_f32_16x16x32_bf16 v[46:49], v[158:161], v[178:181], v[46:49]
	v_mfma_f32_16x16x32_bf16 v[38:41], v[150:153], v[186:189], v[38:41]
	v_mfma_f32_16x16x32_bf16 v[30:33], v[158:161], v[186:189], v[30:33]
	v_mfma_f32_16x16x32_bf16 v[22:25], v[150:153], v[200:203], v[22:25]
	v_mfma_f32_16x16x32_bf16 v[14:17], v[158:161], v[200:203], v[14:17]
	v_mfma_f32_16x16x32_bf16 v[6:9], v[150:153], v[208:211], v[6:9]
	v_mfma_f32_16x16x32_bf16 v[2:5], v[158:161], v[208:211], v[2:5]
	s_setprio 0
	s_barrier
	s_add_i32 s25, s25, 2
	s_add_u32 s54, s54, 0x100
	s_addc_u32 s55, s55, 0
	s_add_u32 s23, s23, 0x100
	s_addc_u32 s24, s24, 0
	s_cmp_gt_u32 s25, 13
	s_cbranch_scc0 .LBB0_165
	s_and_b64 vcc, exec, s[16:17]
	s_cbranch_vccz .LBB0_168
	s_barrier

; #define PG8_STAGE(bufoff, gbase, voff) do { _Pragma("unroll") for (int _i = 0; _i < 2; ++_i) \
;         __builtin_amdgcn_global_load_lds((const unsigned*)((const char*)(gbase) + (voff)[_i]), (PG8_LAS unsigned*)(lds + (bufoff) + ldsw + _i * 8192), 16, 0, 0); } while (0)
; #define PG8_LDA(dst, b, h) do { _Pragma("unroll") for (int m = 0; m < 4; ++m) _Pragma("unroll") for (int k = 0; k < 2; ++k) dst[m][k] = *(const PG8_LAS bf16x8*)(lds + PG8_SA(b, h) + aoff + m * 2048 + k * 1024); } while (0)
; #define PG8_LDB(dst, b, h) do { _Pragma("unroll") for (int n = 0; n < 2; ++n) _Pragma("unroll") for (int k = 0; k < 2; ++k) dst[n][k] = *(const PG8_LAS bf16x8*)(lds + PG8_SB(b, h) + boff + n * 2048 + k * 1024); } while (0)
; #define PG8_MMA(ai, bj, At, Bt) do { __builtin_amdgcn_s_setprio(1); _Pragma("unroll") for (int m = 0; m < 4; ++m) _Pragma("unroll") for (int n = 0; n < 2; ++n) _Pragma("unroll") for (int k = 0; k < 2; ++k) \
;         acc[ai][bj][m][n] = __builtin_amdgcn_mfma_f32_16x16x32_bf16(Bt[n][k], At[m][k], acc[ai][bj][m][n], 0, 0, 0); __builtin_amdgcn_s_setprio(0); } while (0)
; #define PG8_WAIT_V(n) asm volatile("s_waitcnt vmcnt(" #n ")" ::: "memory")
; #define PG8_WAIT_L(n) asm volatile("s_waitcnt lgkmcnt(" #n ")" ::: "memory")
; #define PG8_BAR __builtin_amdgcn_s_barrier()
; #define PG8_SCHED __builtin_amdgcn_sched_barrier(0)
; template <class Epi, class Sched, bool ALIGN_EPI = false, bool SP2 = false, bool SPLITK = false>
; __device__ __forceinline__ void gemm_phase(PG8_LAS unsigned char* lds, const Gemm g, const Sched& S, const Epi& E) {
;     ...
;             PG8_LDB(B0, 0, 0); PG8_LDB(B1, 0, 1); PG8_SCHED; PG8_LDA(At, 0, 0); PG8_STAGE(PG8_SA(1, 1), a1 + hstep, voffA);
;             PG8_WAIT_V(8); PG8_WAIT_L(0); PG8_BAR; PG8_MMA(0, 0, At, B0); PG8_MMA(0, 1, At, B1); PG8_BAR; PG8_SCHED;
;             PG8_LDA(At, 0, 1); PG8_STAGE(PG8_SB(0, 0), b2, voffB); PG8_STAGE(PG8_SB(0, 1), b2 + hstep, voffB); PG8_STAGE(PG8_SA(0, 0), a2, voffA);
;             PG8_WAIT_V(8); PG8_WAIT_L(0); PG8_BAR; PG8_MMA(1, 0, At, B0); PG8_MMA(1, 1, At, B1); PG8_BAR; PG8_SCHED;
.LBB0_431:
	s_add_i32 s12, 0, 0x10000
	v_add_u32_e32 v0, s12, v202
	s_add_i32 s88, 0, 0x14000
	ds_read_b128 v[132:135], v0
	ds_read_b128 v[136:139], v0 offset:1024
	ds_read_b128 v[140:143], v0 offset:2048
	ds_read_b128 v[144:147], v0 offset:3072
	v_add_u32_e32 v0, s88, v202
	ds_read_b128 v[148:151], v0
	ds_read_b128 v[152:155], v0 offset:1024
	ds_read_b128 v[156:159], v0 offset:2048
	ds_read_b128 v[160:163], v0 offset:3072
	s_add_u32 s50, s50, 0x40000
	s_addc_u32 s51, s51, 0
	v_lshl_add_u64 v[2:3], s[50:51], 0, v[192:193]
	s_add_i32 m0, s24, 0xc000
	ds_read_b128 v[164:167], v203
	ds_read_b128 v[168:171], v203 offset:1024
	ds_read_b128 v[172:175], v203 offset:2048
	ds_read_b128 v[176:179], v203 offset:3072
	ds_read_b128 v[180:183], v203 offset:4096
	ds_read_b128 v[184:187], v203 offset:5120
	ds_read_b128 v[188:191], v203 offset:6144
	ds_read_b128 v[204:207], v203 offset:7168
	global_load_lds_dwordx4 v[2:3], off
	v_lshl_add_u64 v[2:3], s[50:51], 0, v[196:197]
	s_add_i32 m0, s24, 0xe000
	s_nop 0
	global_load_lds_dwordx4 v[2:3], off
	s_waitcnt vmcnt(8)
	s_waitcnt lgkmcnt(0)
	s_barrier
	s_setprio 1
	v_mfma_f32_16x16x32_bf16 v[128:131], v[132:135], v[164:167], v[128:131]
	v_mfma_f32_16x16x32_bf16 v[124:127], v[140:143], v[164:167], v[124:127]
	v_mfma_f32_16x16x32_bf16 v[112:115], v[132:135], v[172:175], v[112:115]
	v_mfma_f32_16x16x32_bf16 v[108:111], v[140:143], v[172:175], v[108:111]
	v_mfma_f32_16x16x32_bf16 v[96:99], v[132:135], v[180:183], v[96:99]
	v_mfma_f32_16x16x32_bf16 v[92:95], v[140:143], v[180:183], v[92:95]
	v_mfma_f32_16x16x32_bf16 v[80:83], v[132:135], v[188:191], v[80:83]
	v_mfma_f32_16x16x32_bf16 v[76:79], v[140:143], v[188:191], v[76:79]
	v_mfma_f32_16x16x32_bf16 v[128:131], v[136:139], v[168:171], v[128:131]
	v_mfma_f32_16x16x32_bf16 v[124:127], v[144:147], v[168:171], v[124:127]
	v_mfma_f32_16x16x32_bf16 v[112:115], v[136:139], v[176:179], v[112:115]
	v_mfma_f32_16x16x32_bf16 v[108:111], v[144:147], v[176:179], v[108:111]
	v_mfma_f32_16x16x32_bf16 v[96:99], v[136:139], v[184:187], v[96:99]
	v_mfma_f32_16x16x32_bf16 v[92:95], v[144:147], v[184:187], v[92:95]
	v_mfma_f32_16x16x32_bf16 v[80:83], v[136:139], v[204:207], v[80:83]
	v_mfma_f32_16x16x32_bf16 v[76:79], v[144:147], v[204:207], v[76:79]
	s_setprio 0
	s_setprio 1
	v_mfma_f32_16x16x32_bf16 v[120:123], v[148:151], v[164:167], v[120:123]
	v_mfma_f32_16x16x32_bf16 v[116:119], v[156:159], v[164:167], v[116:119]
	v_mfma_f32_16x16x32_bf16 v[104:107], v[148:151], v[172:175], v[104:107]
	v_mfma_f32_16x16x32_bf16 v[100:103], v[156:159], v[172:175], v[100:103]
	v_mfma_f32_16x16x32_bf16 v[88:91], v[148:151], v[180:183], v[88:91]
	v_mfma_f32_16x16x32_bf16 v[84:87], v[156:159], v[180:183], v[84:87]
	v_mfma_f32_16x16x32_bf16 v[72:75], v[148:151], v[188:191], v[72:75]
	v_mfma_f32_16x16x32_bf16 v[68:71], v[156:159], v[188:191], v[68:71]
	v_mfma_f32_16x16x32_bf16 v[120:123], v[152:155], v[168:171], v[120:123]
	v_mfma_f32_16x16x32_bf16 v[116:119], v[160:163], v[168:171], v[116:119]
	v_mfma_f32_16x16x32_bf16 v[104:107], v[152:155], v[176:179], v[104:107]
	v_mfma_f32_16x16x32_bf16 v[100:103], v[160:163], v[176:179], v[100:103]
	v_mfma_f32_16x16x32_bf16 v[88:91], v[152:155], v[184:187], v[88:91]
	v_mfma_f32_16x16x32_bf16 v[84:87], v[160:163], v[184:187], v[84:87]
	v_mfma_f32_16x16x32_bf16 v[72:75], v[152:155], v[204:207], v[72:75]
	v_mfma_f32_16x16x32_bf16 v[68:71], v[160:163], v[204:207], v[68:71]
	s_setprio 0
	s_barrier
	s_add_i32 s12, s12, s23
	v_lshl_add_u64 v[208:209], s[46:47], 0, v[194:195]
	s_mov_b32 m0, s12
	ds_read_b128 v[164:167], v203 offset:16384
	ds_read_b128 v[168:171], v203 offset:17408
	ds_read_b128 v[172:175], v203 offset:18432
	ds_read_b128 v[176:179], v203 offset:19456
	ds_read_b128 v[180:183], v203 offset:20480
	ds_read_b128 v[184:187], v203 offset:21504
	ds_read_b128 v[188:191], v203 offset:22528
	ds_read_b128 v[204:207], v203 offset:23552
	global_load_lds_dwordx4 v[208:209], off
	s_add_i32 m0, s12, 0x2000
	s_add_u32 s50, s46, 0x40000
	v_lshl_add_u64 v[210:211], s[46:47], 0, v[198:199]
	s_addc_u32 s51, s47, 0
	s_add_i32 s12, s88, s23
	global_load_lds_dwordx4 v[210:211], off
	v_lshl_add_u64 v[2:3], s[50:51], 0, v[194:195]
	s_mov_b32 m0, s12
	v_lshl_add_u64 v[212:213], s[48:49], 0, v[192:193]
	global_load_lds_dwordx4 v[2:3], off
	v_lshl_add_u64 v[2:3], s[50:51], 0, v[198:199]
	s_add_i32 m0, s12, 0x2000
	v_lshl_add_u64 v[214:215], s[48:49], 0, v[196:197]
	global_load_lds_dwordx4 v[2:3], off
	s_mov_b32 m0, s24
	s_nop 0
	global_load_lds_dwordx4 v[212:213], off
	s_mov_b32 m0, s25
	s_nop 0
	global_load_lds_dwordx4 v[214:215], off
	s_waitcnt vmcnt(8)
	s_waitcnt lgkmcnt(0)
	s_barrier
; #define PG8_STAGE(bufoff, gbase, voff) do { _Pragma("unroll") for (int _i = 0; _i < 2; ++_i) \
;         __builtin_amdgcn_global_load_lds((const unsigned*)((const char*)(gbase) + (voff)[_i]), (PG8_LAS unsigned*)(lds + (bufoff) + ldsw + _i * 8192), 16, 0, 0); } while (0)
; #define PG8_LDA(dst, b, h) do { _Pragma("unroll") for (int m = 0; m < 4; ++m) _Pragma("unroll") for (int k = 0; k < 2; ++k) dst[m][k] = *(const PG8_LAS bf16x8*)(lds + PG8_SA(b, h) + aoff + m * 2048 + k * 1024); } while (0)
; #define PG8_LDB(dst, b, h) do { _Pragma("unroll") for (int n = 0; n < 2; ++n) _Pragma("unroll") for (int k = 0; k < 2; ++k) dst[n][k] = *(const PG8_LAS bf16x8*)(lds + PG8_SB(b, h) + boff + n * 2048 + k * 1024); } while (0)
; #define PG8_MMA(ai, bj, At, Bt) do { __builtin_amdgcn_s_setprio(1); _Pragma("unroll") for (int m = 0; m < 4; ++m) _Pragma("unroll") for (int n = 0; n < 2; ++n) _Pragma("unroll") for (int k = 0; k < 2; ++k) \
;         acc[ai][bj][m][n] = __builtin_amdgcn_mfma_f32_16x16x32_bf16(Bt[n][k], At[m][k], acc[ai][bj][m][n], 0, 0, 0); __builtin_amdgcn_s_setprio(0); } while (0)
; #define PG8_WAIT_V(n) asm volatile("s_waitcnt vmcnt(" #n ")" ::: "memory")
; #define PG8_WAIT_L(n) asm volatile("s_waitcnt lgkmcnt(" #n ")" ::: "memory")
; #define PG8_BAR __builtin_amdgcn_s_barrier()
; #define PG8_SCHED __builtin_amdgcn_sched_barrier(0)
; template <class Epi, class Sched, bool ALIGN_EPI = false, bool SP2 = false, bool SPLITK = false>
; __device__ __forceinline__ void gemm_phase(PG8_LAS unsigned char* lds, const Gemm g, const Sched& S, const Epi& E) {
;     ...
;             PG8_WAIT_V(8); PG8_WAIT_L(0); PG8_BAR; PG8_MMA(1, 0, At, B0); PG8_MMA(1, 1, At, B1); PG8_BAR; PG8_SCHED;
;             PG8_LDB(B0, 1, 0); PG8_LDB(B1, 1, 1); PG8_SCHED; PG8_LDA(At, 1, 0); PG8_STAGE(PG8_SA(0, 1), a2 + hstep, voffA);
;             PG8_WAIT_V(8); PG8_WAIT_L(0); PG8_BAR; PG8_MMA(0, 0, At, B0); PG8_MMA(0, 1, At, B1); PG8_BAR; PG8_SCHED;
	s_setprio 1
	v_mfma_f32_16x16x32_bf16 v[64:67], v[132:135], v[164:167], v[64:67]
	v_mfma_f32_16x16x32_bf16 v[60:63], v[140:143], v[164:167], v[60:63]
	v_mfma_f32_16x16x32_bf16 v[48:51], v[132:135], v[172:175], v[48:51]
	v_mfma_f32_16x16x32_bf16 v[44:47], v[140:143], v[172:175], v[44:47]
	v_mfma_f32_16x16x32_bf16 v[32:35], v[132:135], v[180:183], v[32:35]
	v_mfma_f32_16x16x32_bf16 v[28:31], v[140:143], v[180:183], v[28:31]
	v_mfma_f32_16x16x32_bf16 v[16:19], v[132:135], v[188:191], v[16:19]
	v_mfma_f32_16x16x32_bf16 v[12:15], v[140:143], v[188:191], v[12:15]
	v_mfma_f32_16x16x32_bf16 v[64:67], v[136:139], v[168:171], v[64:67]
	v_mfma_f32_16x16x32_bf16 v[60:63], v[144:147], v[168:171], v[60:63]
	v_mfma_f32_16x16x32_bf16 v[48:51], v[136:139], v[176:179], v[48:51]
	v_mfma_f32_16x16x32_bf16 v[44:47], v[144:147], v[176:179], v[44:47]
	v_mfma_f32_16x16x32_bf16 v[32:35], v[136:139], v[184:187], v[32:35]
	v_mfma_f32_16x16x32_bf16 v[28:31], v[144:147], v[184:187], v[28:31]
	v_mfma_f32_16x16x32_bf16 v[16:19], v[136:139], v[204:207], v[16:19]
	v_mfma_f32_16x16x32_bf16 v[12:15], v[144:147], v[204:207], v[12:15]
	s_setprio 0
	s_setprio 1
	v_mfma_f32_16x16x32_bf16 v[56:59], v[148:151], v[164:167], v[56:59]
	v_mfma_f32_16x16x32_bf16 v[52:55], v[156:159], v[164:167], v[52:55]
	v_mfma_f32_16x16x32_bf16 v[40:43], v[148:151], v[172:175], v[40:43]
	v_mfma_f32_16x16x32_bf16 v[36:39], v[156:159], v[172:175], v[36:39]
	v_mfma_f32_16x16x32_bf16 v[24:27], v[148:151], v[180:183], v[24:27]
	v_mfma_f32_16x16x32_bf16 v[20:23], v[156:159], v[180:183], v[20:23]
	v_mfma_f32_16x16x32_bf16 v[8:11], v[148:151], v[188:191], v[8:11]
	v_mfma_f32_16x16x32_bf16 v[2:5], v[156:159], v[188:191], v[4:7]
	v_mfma_f32_16x16x32_bf16 v[56:59], v[152:155], v[168:171], v[56:59]
	v_mfma_f32_16x16x32_bf16 v[52:55], v[160:163], v[168:171], v[52:55]
	v_mfma_f32_16x16x32_bf16 v[40:43], v[152:155], v[176:179], v[40:43]
	v_mfma_f32_16x16x32_bf16 v[36:39], v[160:163], v[176:179], v[36:39]
	v_mfma_f32_16x16x32_bf16 v[24:27], v[152:155], v[184:187], v[24:27]
	v_mfma_f32_16x16x32_bf16 v[20:23], v[160:163], v[184:187], v[20:23]
	v_mfma_f32_16x16x32_bf16 v[8:11], v[152:155], v[204:207], v[8:11]
	v_mfma_f32_16x16x32_bf16 v[2:5], v[160:163], v[204:207], v[2:5]
	s_setprio 0
	s_barrier
	s_add_i32 s12, 0, 0x18000
	v_add_u32_e32 v0, s12, v202
	s_add_i32 s50, 0, 0x1c000
	ds_read_b128 v[132:135], v0
	ds_read_b128 v[136:139], v0 offset:1024
	ds_read_b128 v[140:143], v0 offset:2048
	ds_read_b128 v[144:147], v0 offset:3072
	v_add_u32_e32 v0, s50, v202
	ds_read_b128 v[148:151], v0
	ds_read_b128 v[152:155], v0 offset:1024
	ds_read_b128 v[156:159], v0 offset:2048
	ds_read_b128 v[160:163], v0 offset:3072
	s_add_u32 s48, s48, 0x40000
	s_addc_u32 s49, s49, 0
	s_mov_b32 m0, s33
	v_lshl_add_u64 v[6:7], s[48:49], 0, v[192:193]
	ds_read_b128 v[164:167], v203 offset:32768
	ds_read_b128 v[168:171], v203 offset:33792
	ds_read_b128 v[172:175], v203 offset:34816
	ds_read_b128 v[176:179], v203 offset:35840
	ds_read_b128 v[180:183], v203 offset:36864
	ds_read_b128 v[184:187], v203 offset:37888
	ds_read_b128 v[188:191], v203 offset:38912
	ds_read_b128 v[204:207], v203 offset:39936
	global_load_lds_dwordx4 v[6:7], off
	v_lshl_add_u64 v[6:7], s[48:49], 0, v[196:197]
	s_mov_b32 m0, s64
	s_nop 0
	global_load_lds_dwordx4 v[6:7], off
	s_waitcnt vmcnt(8)
	s_waitcnt lgkmcnt(0)
	s_barrier
	s_setprio 1
	v_mfma_f32_16x16x32_bf16 v[128:131], v[132:135], v[164:167], v[128:131]
	v_mfma_f32_16x16x32_bf16 v[124:127], v[140:143], v[164:167], v[124:127]
	v_mfma_f32_16x16x32_bf16 v[112:115], v[132:135], v[172:175], v[112:115]
	v_mfma_f32_16x16x32_bf16 v[108:111], v[140:143], v[172:175], v[108:111]
	v_mfma_f32_16x16x32_bf16 v[96:99], v[132:135], v[180:183], v[96:99]
	v_mfma_f32_16x16x32_bf16 v[92:95], v[140:143], v[180:183], v[92:95]
	v_mfma_f32_16x16x32_bf16 v[80:83], v[132:135], v[188:191], v[80:83]
	v_mfma_f32_16x16x32_bf16 v[76:79], v[140:143], v[188:191], v[76:79]
	v_mfma_f32_16x16x32_bf16 v[128:131], v[136:139], v[168:171], v[128:131]
	v_mfma_f32_16x16x32_bf16 v[124:127], v[144:147], v[168:171], v[124:127]
	v_mfma_f32_16x16x32_bf16 v[112:115], v[136:139], v[176:179], v[112:115]
	v_mfma_f32_16x16x32_bf16 v[108:111], v[144:147], v[176:179], v[108:111]
	v_mfma_f32_16x16x32_bf16 v[96:99], v[136:139], v[184:187], v[96:99]
	v_mfma_f32_16x16x32_bf16 v[92:95], v[144:147], v[184:187], v[92:95]
	v_mfma_f32_16x16x32_bf16 v[80:83], v[136:139], v[204:207], v[80:83]
	v_mfma_f32_16x16x32_bf16 v[76:79], v[144:147], v[204:207], v[76:79]
	s_setprio 0
	s_setprio 1
	v_mfma_f32_16x16x32_bf16 v[120:123], v[148:151], v[164:167], v[120:123]
	v_mfma_f32_16x16x32_bf16 v[116:119], v[156:159], v[164:167], v[116:119]
	v_mfma_f32_16x16x32_bf16 v[104:107], v[148:151], v[172:175], v[104:107]
	v_mfma_f32_16x16x32_bf16 v[100:103], v[156:159], v[172:175], v[100:103]
	v_mfma_f32_16x16x32_bf16 v[88:91], v[148:151], v[180:183], v[88:91]
	v_mfma_f32_16x16x32_bf16 v[84:87], v[156:159], v[180:183], v[84:87]
	v_mfma_f32_16x16x32_bf16 v[72:75], v[148:151], v[188:191], v[72:75]
	v_mfma_f32_16x16x32_bf16 v[68:71], v[156:159], v[188:191], v[68:71]
	v_mfma_f32_16x16x32_bf16 v[120:123], v[152:155], v[168:171], v[120:123]
	v_mfma_f32_16x16x32_bf16 v[116:119], v[160:163], v[168:171], v[116:119]
	v_mfma_f32_16x16x32_bf16 v[104:107], v[152:155], v[176:179], v[104:107]
	v_mfma_f32_16x16x32_bf16 v[100:103], v[160:163], v[176:179], v[100:103]
	v_mfma_f32_16x16x32_bf16 v[88:91], v[152:155], v[184:187], v[88:91]
	v_mfma_f32_16x16x32_bf16 v[84:87], v[160:163], v[184:187], v[84:87]
	v_mfma_f32_16x16x32_bf16 v[72:75], v[152:155], v[204:207], v[72:75]
	v_mfma_f32_16x16x32_bf16 v[68:71], v[160:163], v[204:207], v[68:71]
	s_setprio 0
	s_barrier
; #define PG8_STAGE(bufoff, gbase, voff) do { _Pragma("unroll") for (int _i = 0; _i < 2; ++_i) \
;         __builtin_amdgcn_global_load_lds((const unsigned*)((const char*)(gbase) + (voff)[_i]), (PG8_LAS unsigned*)(lds + (bufoff) + ldsw + _i * 8192), 16, 0, 0); } while (0)
; #define PG8_LDA(dst, b, h) do { _Pragma("unroll") for (int m = 0; m < 4; ++m) _Pragma("unroll") for (int k = 0; k < 2; ++k) dst[m][k] = *(const PG8_LAS bf16x8*)(lds + PG8_SA(b, h) + aoff + m * 2048 + k * 1024); } while (0)
; #define PG8_MMA(ai, bj, At, Bt) do { __builtin_amdgcn_s_setprio(1); _Pragma("unroll") for (int m = 0; m < 4; ++m) _Pragma("unroll") for (int n = 0; n < 2; ++n) _Pragma("unroll") for (int k = 0; k < 2; ++k) \
;         acc[ai][bj][m][n] = __builtin_amdgcn_mfma_f32_16x16x32_bf16(Bt[n][k], At[m][k], acc[ai][bj][m][n], 0, 0, 0); __builtin_amdgcn_s_setprio(0); } while (0)
; #define PG8_WAIT_V(n) asm volatile("s_waitcnt vmcnt(" #n ")" ::: "memory")
; #define PG8_WAIT_L(n) asm volatile("s_waitcnt lgkmcnt(" #n ")" ::: "memory")
; #define PG8_BAR __builtin_amdgcn_s_barrier()
; #define PG8_SCHED __builtin_amdgcn_sched_barrier(0)
; template <class Epi, class Sched, bool ALIGN_EPI = false, bool SP2 = false, bool SPLITK = false>
; __device__ __forceinline__ void gemm_phase(PG8_LAS unsigned char* lds, const Gemm g, const Sched& S, const Epi& E) {
;     ...
;         for (int t = 0; t < nt; t += 2) {
;             const bool last = (t == nt - 2);
;             if constexpr (SPLITK) { if (t == nt1) E.mid(acc, cur, wr, wc, fr, fq); }
;     ...
;             PG8_LDA(At, 1, 1); PG8_STAGE(PG8_SB(1, 0), b3, voffB); PG8_STAGE(PG8_SB(1, 1), b3 + hstep, voffB); PG8_STAGE(PG8_SA(1, 0), a3, voffA);
;             PG8_WAIT_V(8); PG8_WAIT_L(0); PG8_BAR; PG8_MMA(1, 0, At, B0); PG8_MMA(1, 1, At, B1); PG8_BAR; PG8_SCHED;
	s_add_i32 s12, s12, s23
	v_lshl_add_u64 v[6:7], v[208:209], 0, s[70:71]
	s_mov_b32 m0, s12
	ds_read_b128 v[164:167], v203 offset:49152
	ds_read_b128 v[168:171], v203 offset:50176
	ds_read_b128 v[172:175], v203 offset:51200
	ds_read_b128 v[176:179], v203 offset:52224
	ds_read_b128 v[180:183], v203 offset:53248
	ds_read_b128 v[184:187], v203 offset:54272
	ds_read_b128 v[188:191], v203 offset:55296
	ds_read_b128 v[204:207], v203 offset:56320
	global_load_lds_dwordx4 v[6:7], off
	s_add_i32 m0, s12, 0x2000
	s_add_u32 s46, s46, 0x40080
	v_lshl_add_u64 v[6:7], v[210:211], 0, s[70:71]
	s_addc_u32 s47, s47, 0
	s_add_i32 s12, s50, s23
	global_load_lds_dwordx4 v[6:7], off
	v_lshl_add_u64 v[6:7], s[46:47], 0, v[194:195]
	s_mov_b32 m0, s12
	s_nop 0
	global_load_lds_dwordx4 v[6:7], off
	v_lshl_add_u64 v[6:7], s[46:47], 0, v[198:199]
	s_add_i32 m0, s12, 0x2000
	s_nop 0
	global_load_lds_dwordx4 v[6:7], off
	v_lshl_add_u64 v[6:7], v[212:213], 0, s[70:71]
	s_mov_b32 m0, s65
	s_nop 0
	global_load_lds_dwordx4 v[6:7], off
	v_lshl_add_u64 v[6:7], v[214:215], 0, s[70:71]
	s_mov_b32 m0, s68
	s_nop 0
	global_load_lds_dwordx4 v[6:7], off
	s_waitcnt vmcnt(8)
	s_waitcnt lgkmcnt(0)
	s_barrier
	s_setprio 1
	v_mfma_f32_16x16x32_bf16 v[64:67], v[132:135], v[164:167], v[64:67]
	v_mfma_f32_16x16x32_bf16 v[60:63], v[140:143], v[164:167], v[60:63]
	v_mfma_f32_16x16x32_bf16 v[48:51], v[132:135], v[172:175], v[48:51]
	v_mfma_f32_16x16x32_bf16 v[44:47], v[140:143], v[172:175], v[44:47]
	v_mfma_f32_16x16x32_bf16 v[32:35], v[132:135], v[180:183], v[32:35]
	v_mfma_f32_16x16x32_bf16 v[28:31], v[140:143], v[180:183], v[28:31]
	v_mfma_f32_16x16x32_bf16 v[16:19], v[132:135], v[188:191], v[16:19]
	v_mfma_f32_16x16x32_bf16 v[12:15], v[140:143], v[188:191], v[12:15]
	v_mfma_f32_16x16x32_bf16 v[64:67], v[136:139], v[168:171], v[64:67]
	v_mfma_f32_16x16x32_bf16 v[60:63], v[144:147], v[168:171], v[60:63]
	v_mfma_f32_16x16x32_bf16 v[48:51], v[136:139], v[176:179], v[48:51]
	v_mfma_f32_16x16x32_bf16 v[44:47], v[144:147], v[176:179], v[44:47]
	v_mfma_f32_16x16x32_bf16 v[32:35], v[136:139], v[184:187], v[32:35]
	v_mfma_f32_16x16x32_bf16 v[28:31], v[144:147], v[184:187], v[28:31]
	v_mfma_f32_16x16x32_bf16 v[16:19], v[136:139], v[204:207], v[16:19]
	v_mfma_f32_16x16x32_bf16 v[12:15], v[144:147], v[204:207], v[12:15]
	s_setprio 0
	s_setprio 1
	v_mfma_f32_16x16x32_bf16 v[56:59], v[148:151], v[164:167], v[56:59]
	v_mfma_f32_16x16x32_bf16 v[52:55], v[156:159], v[164:167], v[52:55]
	v_mfma_f32_16x16x32_bf16 v[40:43], v[148:151], v[172:175], v[40:43]
	v_mfma_f32_16x16x32_bf16 v[36:39], v[156:159], v[172:175], v[36:39]
	v_mfma_f32_16x16x32_bf16 v[24:27], v[148:151], v[180:183], v[24:27]
	v_mfma_f32_16x16x32_bf16 v[20:23], v[156:159], v[180:183], v[20:23]
	v_mfma_f32_16x16x32_bf16 v[6:9], v[148:151], v[188:191], v[8:11]
	v_mfma_f32_16x16x32_bf16 v[2:5], v[156:159], v[188:191], v[2:5]
	v_mfma_f32_16x16x32_bf16 v[56:59], v[152:155], v[168:171], v[56:59]
	v_mfma_f32_16x16x32_bf16 v[52:55], v[160:163], v[168:171], v[52:55]
	v_mfma_f32_16x16x32_bf16 v[40:43], v[152:155], v[176:179], v[40:43]
	v_mfma_f32_16x16x32_bf16 v[36:39], v[160:163], v[176:179], v[36:39]
	v_mfma_f32_16x16x32_bf16 v[24:27], v[152:155], v[184:187], v[24:27]
	v_mfma_f32_16x16x32_bf16 v[20:23], v[160:163], v[184:187], v[20:23]
	v_mfma_f32_16x16x32_bf16 v[8:11], v[152:155], v[204:207], v[6:9]
	v_mfma_f32_16x16x32_bf16 v[4:7], v[160:163], v[204:207], v[2:5]
	s_setprio 0
	s_barrier
	s_add_i32 s12, s41, 2
	s_add_u32 s94, s94, 0x100
	s_addc_u32 s95, s95, 0
	s_add_u32 s96, s96, 0x100
	s_addc_u32 s97, s97, 0
	s_cmp_gt_u32 s41, 29
	s_cbranch_scc1 .LBB0_435
	s_mov_b32 s41, s12
	s_cmp_lg_u32 s41, 16
	s_cbranch_scc1 .LBB0_422

; #define PG8_STAGE(bufoff, gbase, voff) do { _Pragma("unroll") for (int _i = 0; _i < 2; ++_i) \
;         __builtin_amdgcn_global_load_lds((const unsigned*)((const char*)(gbase) + (voff)[_i]), (PG8_LAS unsigned*)(lds + (bufoff) + ldsw + _i * 8192), 16, 0, 0); } while (0)
; #define PG8_LDA(dst, b, h) do { _Pragma("unroll") for (int m = 0; m < 4; ++m) _Pragma("unroll") for (int k = 0; k < 2; ++k) dst[m][k] = *(const PG8_LAS bf16x8*)(lds + PG8_SA(b, h) + aoff + m * 2048 + k * 1024); } while (0)
; #define PG8_LDB(dst, b, h) do { _Pragma("unroll") for (int n = 0; n < 2; ++n) _Pragma("unroll") for (int k = 0; k < 2; ++k) dst[n][k] = *(const PG8_LAS bf16x8*)(lds + PG8_SB(b, h) + boff + n * 2048 + k * 1024); } while (0)
; #define PG8_MMA(ai, bj, At, Bt) do { __builtin_amdgcn_s_setprio(1); _Pragma("unroll") for (int m = 0; m < 4; ++m) _Pragma("unroll") for (int n = 0; n < 2; ++n) _Pragma("unroll") for (int k = 0; k < 2; ++k) \
;         acc[ai][bj][m][n] = __builtin_amdgcn_mfma_f32_16x16x32_bf16(Bt[n][k], At[m][k], acc[ai][bj][m][n], 0, 0, 0); __builtin_amdgcn_s_setprio(0); } while (0)
; #define PG8_WAIT_V(n) asm volatile("s_waitcnt vmcnt(" #n ")" ::: "memory")
; #define PG8_WAIT_L(n) asm volatile("s_waitcnt lgkmcnt(" #n ")" ::: "memory")
; #define PG8_BAR __builtin_amdgcn_s_barrier()
; #define PG8_SCHED __builtin_amdgcn_sched_barrier(0)
; template <class Epi, class Sched, bool ALIGN_EPI = false, bool SP2 = false, bool SPLITK = false>
; __device__ __forceinline__ void gemm_phase(PG8_LAS unsigned char* lds, const Gemm g, const Sched& S, const Epi& E) {
;     ...
;             const char* a1 = PG8_TA(t + 1);
;             const char* a2 = last ? nA : PG8_TA(t + 2); const char* b2 = last ? nB : PG8_TB(t + 2);
;             const char* a3 = a2 + kstep; const char* b3 = b2 + kstep;
;             if (last && has_next) S.a_ready(nxt);
;             if constexpr (SP2) {
;             PG8_LDB(B0, 0, 0); PG8_LDB(B1, 0, 1); PG8_SCHED; PG8_LDA(At, 0, 0); PG8_STAGE(PG8_SA(1, 1), a1 + hstep, voffA);
;             PG8_WAIT_V(8); PG8_WAIT_L(0); PG8_BAR; PG8_MMA(0, 0, At, B0); PG8_MMA(0, 1, At, B1); PG8_BAR; PG8_SCHED;
;             PG8_LDA(At, 0, 1); PG8_STAGE(PG8_SB(0, 0), b2, voffB); PG8_STAGE(PG8_SB(0, 1), b2 + hstep, voffB); PG8_STAGE(PG8_SA(0, 0), a2, voffA);
;             PG8_WAIT_V(8); PG8_WAIT_L(0); PG8_BAR; PG8_MMA(1, 0, At, B0); PG8_MMA(1, 1, At, B1); PG8_BAR; PG8_SCHED;
.LBB0_510:
	s_add_u32 s46, s52, 0xfffc0080
	s_addc_u32 s47, s53, -1
	s_add_i32 s59, 0, 0x10000
	s_cmp_eq_u32 s58, 12
	s_cselect_b32 s49, s12, s47
	s_cselect_b32 s48, s19, s46
	s_cselect_b32 s47, s21, s45
	s_cselect_b32 s46, s35, s43
	s_add_i32 s68, 0, 0x14000
	v_add_u32_e32 v118, s59, v224
	v_add_u32_e32 v150, s68, v224
	ds_read_b128 v[82:85], v118
	ds_read_b128 v[94:97], v118 offset:1024
	ds_read_b128 v[106:109], v118 offset:2048
	ds_read_b128 v[118:121], v118 offset:3072
	ds_read_b128 v[130:133], v150
	ds_read_b128 v[142:145], v150 offset:1024
	ds_read_b128 v[146:149], v150 offset:2048
	ds_read_b128 v[150:153], v150 offset:3072
	s_add_i32 m0, s25, 0xc000
	ds_read_b128 v[162:165], v225
	ds_read_b128 v[166:169], v225 offset:1024
	ds_read_b128 v[170:173], v225 offset:2048
	ds_read_b128 v[174:177], v225 offset:3072
	ds_read_b128 v[178:181], v225 offset:4096
	ds_read_b128 v[182:185], v225 offset:5120
	ds_read_b128 v[186:189], v225 offset:6144
	ds_read_b128 v[190:193], v225 offset:7168
	global_load_lds_dwordx4 v200, s[52:53]
	s_add_i32 m0, s25, 0xe000
	s_nop 0
	global_load_lds_dwordx4 v202, s[52:53]
	s_waitcnt vmcnt(8)
	s_waitcnt lgkmcnt(0)
	s_barrier
	s_setprio 1
	v_mfma_f32_16x16x32_bf16 v[158:161], v[82:85], v[162:165], v[158:161]
	v_mfma_f32_16x16x32_bf16 v[154:157], v[106:109], v[162:165], v[154:157]
	v_mfma_f32_16x16x32_bf16 v[126:129], v[82:85], v[170:173], v[126:129]
	v_mfma_f32_16x16x32_bf16 v[122:125], v[106:109], v[170:173], v[122:125]
	v_mfma_f32_16x16x32_bf16 v[102:105], v[82:85], v[178:181], v[102:105]
	v_mfma_f32_16x16x32_bf16 v[98:101], v[106:109], v[178:181], v[98:101]
	v_mfma_f32_16x16x32_bf16 v[78:81], v[82:85], v[186:189], v[78:81]
	v_mfma_f32_16x16x32_bf16 v[74:77], v[106:109], v[186:189], v[74:77]
	v_mfma_f32_16x16x32_bf16 v[158:161], v[94:97], v[166:169], v[158:161]
	v_mfma_f32_16x16x32_bf16 v[154:157], v[118:121], v[166:169], v[154:157]
	v_mfma_f32_16x16x32_bf16 v[126:129], v[94:97], v[174:177], v[126:129]
	v_mfma_f32_16x16x32_bf16 v[122:125], v[118:121], v[174:177], v[122:125]
	v_mfma_f32_16x16x32_bf16 v[102:105], v[94:97], v[182:185], v[102:105]
	v_mfma_f32_16x16x32_bf16 v[98:101], v[118:121], v[182:185], v[98:101]
	v_mfma_f32_16x16x32_bf16 v[78:81], v[94:97], v[190:193], v[78:81]
	v_mfma_f32_16x16x32_bf16 v[74:77], v[118:121], v[190:193], v[74:77]
	v_mfma_f32_16x16x32_bf16 v[138:141], v[130:133], v[162:165], v[138:141]
	v_mfma_f32_16x16x32_bf16 v[134:137], v[146:149], v[162:165], v[134:137]
	v_mfma_f32_16x16x32_bf16 v[114:117], v[130:133], v[170:173], v[114:117]
	v_mfma_f32_16x16x32_bf16 v[110:113], v[146:149], v[170:173], v[110:113]
	v_mfma_f32_16x16x32_bf16 v[90:93], v[130:133], v[178:181], v[90:93]
	v_mfma_f32_16x16x32_bf16 v[86:89], v[146:149], v[178:181], v[86:89]
	v_mfma_f32_16x16x32_bf16 v[70:73], v[130:133], v[186:189], v[70:73]
	v_mfma_f32_16x16x32_bf16 v[66:69], v[146:149], v[186:189], v[66:69]
	v_mfma_f32_16x16x32_bf16 v[138:141], v[142:145], v[166:169], v[138:141]
	v_mfma_f32_16x16x32_bf16 v[134:137], v[150:153], v[166:169], v[134:137]
	v_mfma_f32_16x16x32_bf16 v[114:117], v[142:145], v[174:177], v[114:117]
	v_mfma_f32_16x16x32_bf16 v[110:113], v[150:153], v[174:177], v[110:113]
	v_mfma_f32_16x16x32_bf16 v[90:93], v[142:145], v[182:185], v[90:93]
	v_mfma_f32_16x16x32_bf16 v[86:89], v[150:153], v[182:185], v[86:89]
	v_mfma_f32_16x16x32_bf16 v[70:73], v[142:145], v[190:193], v[70:73]
	v_mfma_f32_16x16x32_bf16 v[66:69], v[150:153], v[190:193], v[66:69]
	s_setprio 0
	s_barrier
	s_add_i32 s59, s59, s24
	s_mov_b32 m0, s59
	ds_read_b128 v[162:165], v225 offset:16384
	ds_read_b128 v[166:169], v225 offset:17408
	ds_read_b128 v[170:173], v225 offset:18432
	ds_read_b128 v[174:177], v225 offset:19456
	ds_read_b128 v[178:181], v225 offset:20480
	ds_read_b128 v[182:185], v225 offset:21504
	ds_read_b128 v[186:189], v225 offset:22528
	ds_read_b128 v[190:193], v225 offset:23552
	global_load_lds_dwordx4 v0, s[46:47]
	s_add_i32 m0, s59, 0x2000
	s_add_u32 s64, s46, 0x40000
	s_addc_u32 s65, s47, 0
	s_add_i32 s59, s68, s24
	global_load_lds_dwordx4 v198, s[46:47]
	s_mov_b32 m0, s59
	s_nop 0
	global_load_lds_dwordx4 v0, s[64:65]
	s_add_i32 m0, s59, 0x2000
	s_nop 0
	global_load_lds_dwordx4 v198, s[64:65]
	s_mov_b32 m0, s25
	s_nop 0
	global_load_lds_dwordx4 v194, s[48:49]
	s_mov_b32 m0, s33
	s_nop 0
	global_load_lds_dwordx4 v196, s[48:49]
	s_waitcnt vmcnt(8)
	s_waitcnt lgkmcnt(0)
	s_barrier
	s_setprio 1
	v_mfma_f32_16x16x32_bf16 v[62:65], v[82:85], v[162:165], v[62:65]
	v_mfma_f32_16x16x32_bf16 v[58:61], v[106:109], v[162:165], v[58:61]
	v_mfma_f32_16x16x32_bf16 v[46:49], v[82:85], v[170:173], v[46:49]
	v_mfma_f32_16x16x32_bf16 v[42:45], v[106:109], v[170:173], v[42:45]
	v_mfma_f32_16x16x32_bf16 v[30:33], v[82:85], v[178:181], v[30:33]
	v_mfma_f32_16x16x32_bf16 v[26:29], v[106:109], v[178:181], v[26:29]
	v_mfma_f32_16x16x32_bf16 v[14:17], v[82:85], v[186:189], v[14:17]
	v_mfma_f32_16x16x32_bf16 v[10:13], v[106:109], v[186:189], v[10:13]
	v_mfma_f32_16x16x32_bf16 v[62:65], v[94:97], v[166:169], v[62:65]
	v_mfma_f32_16x16x32_bf16 v[58:61], v[118:121], v[166:169], v[58:61]
	v_mfma_f32_16x16x32_bf16 v[46:49], v[94:97], v[174:177], v[46:49]
	v_mfma_f32_16x16x32_bf16 v[42:45], v[118:121], v[174:177], v[42:45]
	v_mfma_f32_16x16x32_bf16 v[30:33], v[94:97], v[182:185], v[30:33]
	v_mfma_f32_16x16x32_bf16 v[26:29], v[118:121], v[182:185], v[26:29]
	v_mfma_f32_16x16x32_bf16 v[14:17], v[94:97], v[190:193], v[14:17]
	v_mfma_f32_16x16x32_bf16 v[10:13], v[118:121], v[190:193], v[10:13]
	v_mfma_f32_16x16x32_bf16 v[54:57], v[130:133], v[162:165], v[54:57]
	v_mfma_f32_16x16x32_bf16 v[50:53], v[146:149], v[162:165], v[50:53]
	v_mfma_f32_16x16x32_bf16 v[38:41], v[130:133], v[170:173], v[38:41]
	v_mfma_f32_16x16x32_bf16 v[34:37], v[146:149], v[170:173], v[34:37]
	v_mfma_f32_16x16x32_bf16 v[22:25], v[130:133], v[178:181], v[22:25]
	v_mfma_f32_16x16x32_bf16 v[18:21], v[146:149], v[178:181], v[18:21]
	v_mfma_f32_16x16x32_bf16 v[6:9], v[130:133], v[186:189], v[6:9]
	v_mfma_f32_16x16x32_bf16 v[2:5], v[146:149], v[186:189], v[2:5]
	v_mfma_f32_16x16x32_bf16 v[54:57], v[142:145], v[166:169], v[54:57]
	v_mfma_f32_16x16x32_bf16 v[50:53], v[150:153], v[166:169], v[50:53]
	v_mfma_f32_16x16x32_bf16 v[38:41], v[142:145], v[174:177], v[38:41]
	v_mfma_f32_16x16x32_bf16 v[34:37], v[150:153], v[174:177], v[34:37]
	v_mfma_f32_16x16x32_bf16 v[22:25], v[142:145], v[182:185], v[22:25]
	v_mfma_f32_16x16x32_bf16 v[18:21], v[150:153], v[182:185], v[18:21]
	v_mfma_f32_16x16x32_bf16 v[6:9], v[142:145], v[190:193], v[6:9]
	v_mfma_f32_16x16x32_bf16 v[2:5], v[150:153], v[190:193], v[2:5]
	s_setprio 0
	s_barrier
; #define PG8_STAGE(bufoff, gbase, voff) do { _Pragma("unroll") for (int _i = 0; _i < 2; ++_i) \
;         __builtin_amdgcn_global_load_lds((const unsigned*)((const char*)(gbase) + (voff)[_i]), (PG8_LAS unsigned*)(lds + (bufoff) + ldsw + _i * 8192), 16, 0, 0); } while (0)
; #define PG8_LDA(dst, b, h) do { _Pragma("unroll") for (int m = 0; m < 4; ++m) _Pragma("unroll") for (int k = 0; k < 2; ++k) dst[m][k] = *(const PG8_LAS bf16x8*)(lds + PG8_SA(b, h) + aoff + m * 2048 + k * 1024); } while (0)
; #define PG8_LDB(dst, b, h) do { _Pragma("unroll") for (int n = 0; n < 2; ++n) _Pragma("unroll") for (int k = 0; k < 2; ++k) dst[n][k] = *(const PG8_LAS bf16x8*)(lds + PG8_SB(b, h) + boff + n * 2048 + k * 1024); } while (0)
; #define PG8_MMA(ai, bj, At, Bt) do { __builtin_amdgcn_s_setprio(1); _Pragma("unroll") for (int m = 0; m < 4; ++m) _Pragma("unroll") for (int n = 0; n < 2; ++n) _Pragma("unroll") for (int k = 0; k < 2; ++k) \
;         acc[ai][bj][m][n] = __builtin_amdgcn_mfma_f32_16x16x32_bf16(Bt[n][k], At[m][k], acc[ai][bj][m][n], 0, 0, 0); __builtin_amdgcn_s_setprio(0); } while (0)
; #define PG8_WAIT_V(n) asm volatile("s_waitcnt vmcnt(" #n ")" ::: "memory")
; #define PG8_WAIT_L(n) asm volatile("s_waitcnt lgkmcnt(" #n ")" ::: "memory")
; #define PG8_BAR __builtin_amdgcn_s_barrier()
; #define PG8_SCHED __builtin_amdgcn_sched_barrier(0)
; template <class Epi, class Sched, bool ALIGN_EPI = false, bool SP2 = false, bool SPLITK = false>
; __device__ __forceinline__ void gemm_phase(PG8_LAS unsigned char* lds, const Gemm g, const Sched& S, const Epi& E) {
;     ...
;             PG8_LDB(B0, 1, 0); PG8_LDB(B1, 1, 1); PG8_SCHED; PG8_LDA(At, 1, 0); PG8_STAGE(PG8_SA(0, 1), a2 + hstep, voffA);
;             PG8_WAIT_V(8); PG8_WAIT_L(0); PG8_BAR; PG8_MMA(0, 0, At, B0); PG8_MMA(0, 1, At, B1); PG8_BAR; PG8_SCHED;
;             PG8_LDA(At, 1, 1); PG8_STAGE(PG8_SB(1, 0), b3, voffB); PG8_STAGE(PG8_SB(1, 1), b3 + hstep, voffB); PG8_STAGE(PG8_SA(1, 0), a3, voffA);
;             PG8_WAIT_V(8); PG8_WAIT_L(0); PG8_BAR; PG8_MMA(1, 0, At, B0); PG8_MMA(1, 1, At, B1); PG8_BAR; PG8_SCHED;
;     ...
;         if constexpr (ALIGN_EPI) { if (wr == 0) PG8_BAR; }
	s_add_i32 s59, 0, 0x18000
	s_add_i32 s64, 0, 0x1c000
	v_add_u32_e32 v118, s59, v224
	v_add_u32_e32 v150, s64, v224
	ds_read_b128 v[82:85], v118
	ds_read_b128 v[94:97], v118 offset:1024
	ds_read_b128 v[106:109], v118 offset:2048
	ds_read_b128 v[118:121], v118 offset:3072
	ds_read_b128 v[130:133], v150
	ds_read_b128 v[142:145], v150 offset:1024
	ds_read_b128 v[146:149], v150 offset:2048
	ds_read_b128 v[150:153], v150 offset:3072
	s_add_u32 vcc_lo, s48, 0x80
	s_addc_u32 vcc_hi, s49, 0
	s_add_u32 s48, s48, 0x40000
	s_addc_u32 s49, s49, 0
	s_mov_b32 m0, s50
	ds_read_b128 v[162:165], v225 offset:32768
	ds_read_b128 v[166:169], v225 offset:33792
	ds_read_b128 v[170:173], v225 offset:34816
	ds_read_b128 v[174:177], v225 offset:35840
	ds_read_b128 v[178:181], v225 offset:36864
	ds_read_b128 v[182:185], v225 offset:37888
	ds_read_b128 v[186:189], v225 offset:38912
	ds_read_b128 v[190:193], v225 offset:39936
	global_load_lds_dwordx4 v194, s[48:49]
	s_mov_b32 m0, s51
	s_nop 0
	global_load_lds_dwordx4 v196, s[48:49]
	s_waitcnt vmcnt(8)
	s_waitcnt lgkmcnt(0)
	s_barrier
	s_setprio 1
	v_mfma_f32_16x16x32_bf16 v[158:161], v[82:85], v[162:165], v[158:161]
	v_mfma_f32_16x16x32_bf16 v[154:157], v[106:109], v[162:165], v[154:157]
	v_mfma_f32_16x16x32_bf16 v[126:129], v[82:85], v[170:173], v[126:129]
	v_mfma_f32_16x16x32_bf16 v[122:125], v[106:109], v[170:173], v[122:125]
	v_mfma_f32_16x16x32_bf16 v[102:105], v[82:85], v[178:181], v[102:105]
	v_mfma_f32_16x16x32_bf16 v[98:101], v[106:109], v[178:181], v[98:101]
	v_mfma_f32_16x16x32_bf16 v[78:81], v[82:85], v[186:189], v[78:81]
	v_mfma_f32_16x16x32_bf16 v[74:77], v[106:109], v[186:189], v[74:77]
	v_mfma_f32_16x16x32_bf16 v[158:161], v[94:97], v[166:169], v[158:161]
	v_mfma_f32_16x16x32_bf16 v[154:157], v[118:121], v[166:169], v[154:157]
	v_mfma_f32_16x16x32_bf16 v[126:129], v[94:97], v[174:177], v[126:129]
	v_mfma_f32_16x16x32_bf16 v[122:125], v[118:121], v[174:177], v[122:125]
	v_mfma_f32_16x16x32_bf16 v[102:105], v[94:97], v[182:185], v[102:105]
	v_mfma_f32_16x16x32_bf16 v[98:101], v[118:121], v[182:185], v[98:101]
	v_mfma_f32_16x16x32_bf16 v[78:81], v[94:97], v[190:193], v[78:81]
	v_mfma_f32_16x16x32_bf16 v[74:77], v[118:121], v[190:193], v[74:77]
	v_mfma_f32_16x16x32_bf16 v[138:141], v[130:133], v[162:165], v[138:141]
	v_mfma_f32_16x16x32_bf16 v[134:137], v[146:149], v[162:165], v[134:137]
	v_mfma_f32_16x16x32_bf16 v[114:117], v[130:133], v[170:173], v[114:117]
	v_mfma_f32_16x16x32_bf16 v[110:113], v[146:149], v[170:173], v[110:113]
	v_mfma_f32_16x16x32_bf16 v[90:93], v[130:133], v[178:181], v[90:93]
	v_mfma_f32_16x16x32_bf16 v[86:89], v[146:149], v[178:181], v[86:89]
	v_mfma_f32_16x16x32_bf16 v[70:73], v[130:133], v[186:189], v[70:73]
	v_mfma_f32_16x16x32_bf16 v[66:69], v[146:149], v[186:189], v[66:69]
	v_mfma_f32_16x16x32_bf16 v[138:141], v[142:145], v[166:169], v[138:141]
	v_mfma_f32_16x16x32_bf16 v[134:137], v[150:153], v[166:169], v[134:137]
	v_mfma_f32_16x16x32_bf16 v[114:117], v[142:145], v[174:177], v[114:117]
	v_mfma_f32_16x16x32_bf16 v[110:113], v[150:153], v[174:177], v[110:113]
	v_mfma_f32_16x16x32_bf16 v[90:93], v[142:145], v[182:185], v[90:93]
	v_mfma_f32_16x16x32_bf16 v[86:89], v[150:153], v[182:185], v[86:89]
	v_mfma_f32_16x16x32_bf16 v[70:73], v[142:145], v[190:193], v[70:73]
	v_mfma_f32_16x16x32_bf16 v[66:69], v[150:153], v[190:193], v[66:69]
	s_setprio 0
	s_barrier
	s_add_i32 s48, s59, s24
	s_add_u32 s46, s46, 0x80
	s_addc_u32 s47, s47, 0
	s_mov_b32 m0, s48
	ds_read_b128 v[162:165], v225 offset:49152
	ds_read_b128 v[166:169], v225 offset:50176
	ds_read_b128 v[170:173], v225 offset:51200
	ds_read_b128 v[174:177], v225 offset:52224
	ds_read_b128 v[178:181], v225 offset:53248
	ds_read_b128 v[182:185], v225 offset:54272
	ds_read_b128 v[186:189], v225 offset:55296
	ds_read_b128 v[190:193], v225 offset:56320
	global_load_lds_dwordx4 v0, s[46:47]
	s_add_i32 m0, s48, 0x2000
	s_add_i32 s48, s64, s24
	global_load_lds_dwordx4 v198, s[46:47]
	s_add_u32 s46, s46, 0x40000
	s_addc_u32 s47, s47, 0
	s_mov_b32 m0, s48
	s_nop 0
	global_load_lds_dwordx4 v0, s[46:47]
	s_add_i32 m0, s48, 0x2000
	s_nop 0
	global_load_lds_dwordx4 v198, s[46:47]
	s_mov_b32 m0, s54
	s_nop 0
	global_load_lds_dwordx4 v194, vcc
	s_mov_b32 m0, s55
	s_nop 0
	global_load_lds_dwordx4 v196, vcc
	s_waitcnt vmcnt(8)
	s_waitcnt lgkmcnt(0)
	s_barrier
	s_setprio 1
	v_mfma_f32_16x16x32_bf16 v[62:65], v[82:85], v[162:165], v[62:65]
	v_mfma_f32_16x16x32_bf16 v[58:61], v[106:109], v[162:165], v[58:61]
	v_mfma_f32_16x16x32_bf16 v[46:49], v[82:85], v[170:173], v[46:49]
	v_mfma_f32_16x16x32_bf16 v[42:45], v[106:109], v[170:173], v[42:45]
	v_mfma_f32_16x16x32_bf16 v[30:33], v[82:85], v[178:181], v[30:33]
	v_mfma_f32_16x16x32_bf16 v[26:29], v[106:109], v[178:181], v[26:29]
	v_mfma_f32_16x16x32_bf16 v[14:17], v[82:85], v[186:189], v[14:17]
	v_mfma_f32_16x16x32_bf16 v[10:13], v[106:109], v[186:189], v[10:13]
	v_mfma_f32_16x16x32_bf16 v[62:65], v[94:97], v[166:169], v[62:65]
	v_mfma_f32_16x16x32_bf16 v[58:61], v[118:121], v[166:169], v[58:61]
	v_mfma_f32_16x16x32_bf16 v[46:49], v[94:97], v[174:177], v[46:49]
	v_mfma_f32_16x16x32_bf16 v[42:45], v[118:121], v[174:177], v[42:45]
	v_mfma_f32_16x16x32_bf16 v[30:33], v[94:97], v[182:185], v[30:33]
	v_mfma_f32_16x16x32_bf16 v[26:29], v[118:121], v[182:185], v[26:29]
	v_mfma_f32_16x16x32_bf16 v[14:17], v[94:97], v[190:193], v[14:17]
	v_mfma_f32_16x16x32_bf16 v[10:13], v[118:121], v[190:193], v[10:13]
	v_mfma_f32_16x16x32_bf16 v[54:57], v[130:133], v[162:165], v[54:57]
	v_mfma_f32_16x16x32_bf16 v[50:53], v[146:149], v[162:165], v[50:53]
	v_mfma_f32_16x16x32_bf16 v[38:41], v[130:133], v[170:173], v[38:41]
	v_mfma_f32_16x16x32_bf16 v[34:37], v[146:149], v[170:173], v[34:37]
	v_mfma_f32_16x16x32_bf16 v[22:25], v[130:133], v[178:181], v[22:25]
	v_mfma_f32_16x16x32_bf16 v[18:21], v[146:149], v[178:181], v[18:21]
	v_mfma_f32_16x16x32_bf16 v[6:9], v[130:133], v[186:189], v[6:9]
	v_mfma_f32_16x16x32_bf16 v[2:5], v[146:149], v[186:189], v[2:5]
	v_mfma_f32_16x16x32_bf16 v[54:57], v[142:145], v[166:169], v[54:57]
	v_mfma_f32_16x16x32_bf16 v[50:53], v[150:153], v[166:169], v[50:53]
	v_mfma_f32_16x16x32_bf16 v[38:41], v[142:145], v[174:177], v[38:41]
	v_mfma_f32_16x16x32_bf16 v[34:37], v[150:153], v[174:177], v[34:37]
	v_mfma_f32_16x16x32_bf16 v[22:25], v[142:145], v[182:185], v[22:25]
	v_mfma_f32_16x16x32_bf16 v[18:21], v[150:153], v[182:185], v[18:21]
	v_mfma_f32_16x16x32_bf16 v[6:9], v[142:145], v[190:193], v[6:9]
	v_mfma_f32_16x16x32_bf16 v[2:5], v[150:153], v[190:193], v[2:5]
	s_setprio 0
	s_barrier
	s_add_i32 s58, s58, 2
	s_add_u32 s52, s52, 0x100
	s_addc_u32 s53, s53, 0
	s_add_u32 s43, s43, 0x100
	s_addc_u32 s45, s45, 0
	s_cmp_gt_u32 s58, 13
	s_cbranch_scc0 .LBB0_510
	s_and_b64 vcc, exec, s[16:17]
	s_cbranch_vccz .LBB0_513
	s_barrier

; #define PG8_STAGE(bufoff, gbase, voff) do { _Pragma("unroll") for (int _i = 0; _i < 2; ++_i) \
;         __builtin_amdgcn_global_load_lds((const unsigned*)((const char*)(gbase) + (voff)[_i]), (PG8_LAS unsigned*)(lds + (bufoff) + ldsw + _i * 8192), 16, 0, 0); } while (0)
; #define PG8_LDA(dst, b, h) do { _Pragma("unroll") for (int m = 0; m < 4; ++m) _Pragma("unroll") for (int k = 0; k < 2; ++k) dst[m][k] = *(const PG8_LAS bf16x8*)(lds + PG8_SA(b, h) + aoff + m * 2048 + k * 1024); } while (0)
; #define PG8_LDB(dst, b, h) do { _Pragma("unroll") for (int n = 0; n < 2; ++n) _Pragma("unroll") for (int k = 0; k < 2; ++k) dst[n][k] = *(const PG8_LAS bf16x8*)(lds + PG8_SB(b, h) + boff + n * 2048 + k * 1024); } while (0)
; #define PG8_MMA(ai, bj, At, Bt) do { __builtin_amdgcn_s_setprio(1); _Pragma("unroll") for (int m = 0; m < 4; ++m) _Pragma("unroll") for (int n = 0; n < 2; ++n) _Pragma("unroll") for (int k = 0; k < 2; ++k) \
;         acc[ai][bj][m][n] = __builtin_amdgcn_mfma_f32_16x16x32_bf16(Bt[n][k], At[m][k], acc[ai][bj][m][n], 0, 0, 0); __builtin_amdgcn_s_setprio(0); } while (0)
; #define PG8_WAIT_V(n) asm volatile("s_waitcnt vmcnt(" #n ")" ::: "memory")
; #define PG8_WAIT_L(n) asm volatile("s_waitcnt lgkmcnt(" #n ")" ::: "memory")
; #define PG8_BAR __builtin_amdgcn_s_barrier()
; #define PG8_SCHED __builtin_amdgcn_sched_barrier(0)
; template <class Epi, class Sched, bool ALIGN_EPI = false, bool SP2 = false, bool SPLITK = false>
; __device__ __forceinline__ void gemm_phase(PG8_LAS unsigned char* lds, const Gemm g, const Sched& S, const Epi& E) {
;     ...
;             const char* a1 = PG8_TA(t + 1);
;             const char* a2 = last ? nA : PG8_TA(t + 2); const char* b2 = last ? nB : PG8_TB(t + 2);
;             const char* a3 = a2 + kstep; const char* b3 = b2 + kstep;
;             if (last && has_next) S.a_ready(nxt);
;             if constexpr (SP2) {
;             PG8_LDB(B0, 0, 0); PG8_LDB(B1, 0, 1); PG8_SCHED; PG8_LDA(At, 0, 0); PG8_STAGE(PG8_SA(1, 1), a1 + hstep, voffA);
;             PG8_WAIT_V(8); PG8_WAIT_L(0); PG8_BAR; PG8_MMA(0, 0, At, B0); PG8_MMA(0, 1, At, B1); PG8_BAR; PG8_SCHED;
;             PG8_LDA(At, 0, 1); PG8_STAGE(PG8_SB(0, 0), b2, voffB); PG8_STAGE(PG8_SB(0, 1), b2 + hstep, voffB); PG8_STAGE(PG8_SA(0, 0), a2, voffA);
;             PG8_WAIT_V(8); PG8_WAIT_L(0); PG8_BAR; PG8_MMA(1, 0, At, B0); PG8_MMA(1, 1, At, B1); PG8_BAR; PG8_SCHED;
.LBB0_582:
	s_add_u32 s46, s42, 0xfffc0080
	s_addc_u32 s47, s43, -1
	s_add_i32 s64, 0, 0x10000
	s_cmp_eq_u32 s45, 12
	s_cselect_b32 s49, s4, s47
	s_cselect_b32 s48, s12, s46
	s_cselect_b32 s47, s19, s41
	s_cselect_b32 s46, s21, s25
	s_add_i32 s68, 0, 0x14000
	v_add_u32_e32 v142, s64, v181
	v_add_u32_e32 v168, s68, v181
	ds_read_b128 v[130:133], v142
	ds_read_b128 v[134:137], v142 offset:1024
	ds_read_b128 v[138:141], v142 offset:2048
	ds_read_b128 v[142:145], v142 offset:3072
	ds_read_b128 v[156:159], v168
	ds_read_b128 v[160:163], v168 offset:1024
	ds_read_b128 v[164:167], v168 offset:2048
	ds_read_b128 v[170:173], v168 offset:3072
	s_add_i32 m0, s51, 0xc000
	ds_read_b128 v[176:179], v186
	ds_read_b128 v[182:185], v186 offset:1024
	ds_read_b128 v[188:191], v186 offset:2048
	ds_read_b128 v[192:195], v186 offset:3072
	ds_read_b128 v[196:199], v186 offset:4096
	ds_read_b128 v[200:203], v186 offset:5120
	ds_read_b128 v[204:207], v186 offset:6144
	ds_read_b128 v[208:211], v186 offset:7168
	global_load_lds_dwordx4 v152, s[42:43]
	s_add_i32 m0, s51, 0xe000
	s_nop 0
	global_load_lds_dwordx4 v154, s[42:43]
	s_waitcnt vmcnt(8)
	s_waitcnt lgkmcnt(0)
	s_barrier
	s_setprio 1
	v_mfma_f32_16x16x32_bf16 v[126:129], v[130:133], v[176:179], v[126:129]
	v_mfma_f32_16x16x32_bf16 v[118:121], v[138:141], v[176:179], v[118:121]
	v_mfma_f32_16x16x32_bf16 v[110:113], v[130:133], v[188:191], v[110:113]
	v_mfma_f32_16x16x32_bf16 v[102:105], v[138:141], v[188:191], v[102:105]
	v_mfma_f32_16x16x32_bf16 v[94:97], v[130:133], v[196:199], v[94:97]
	v_mfma_f32_16x16x32_bf16 v[86:89], v[138:141], v[196:199], v[86:89]
	v_mfma_f32_16x16x32_bf16 v[78:81], v[130:133], v[204:207], v[78:81]
	v_mfma_f32_16x16x32_bf16 v[70:73], v[138:141], v[204:207], v[70:73]
	v_mfma_f32_16x16x32_bf16 v[126:129], v[134:137], v[182:185], v[126:129]
	v_mfma_f32_16x16x32_bf16 v[118:121], v[142:145], v[182:185], v[118:121]
	v_mfma_f32_16x16x32_bf16 v[110:113], v[134:137], v[192:195], v[110:113]
	v_mfma_f32_16x16x32_bf16 v[102:105], v[142:145], v[192:195], v[102:105]
	v_mfma_f32_16x16x32_bf16 v[94:97], v[134:137], v[200:203], v[94:97]
	v_mfma_f32_16x16x32_bf16 v[86:89], v[142:145], v[200:203], v[86:89]
	v_mfma_f32_16x16x32_bf16 v[78:81], v[134:137], v[208:211], v[78:81]
	v_mfma_f32_16x16x32_bf16 v[70:73], v[142:145], v[208:211], v[70:73]
	v_mfma_f32_16x16x32_bf16 v[122:125], v[156:159], v[176:179], v[122:125]
	v_mfma_f32_16x16x32_bf16 v[114:117], v[164:167], v[176:179], v[114:117]
	v_mfma_f32_16x16x32_bf16 v[106:109], v[156:159], v[188:191], v[106:109]
	v_mfma_f32_16x16x32_bf16 v[98:101], v[164:167], v[188:191], v[98:101]
	v_mfma_f32_16x16x32_bf16 v[90:93], v[156:159], v[196:199], v[90:93]
	v_mfma_f32_16x16x32_bf16 v[82:85], v[164:167], v[196:199], v[82:85]
	v_mfma_f32_16x16x32_bf16 v[74:77], v[156:159], v[204:207], v[74:77]
	v_mfma_f32_16x16x32_bf16 v[66:69], v[164:167], v[204:207], v[66:69]
	v_mfma_f32_16x16x32_bf16 v[122:125], v[160:163], v[182:185], v[122:125]
	v_mfma_f32_16x16x32_bf16 v[114:117], v[170:173], v[182:185], v[114:117]
	v_mfma_f32_16x16x32_bf16 v[106:109], v[160:163], v[192:195], v[106:109]
	v_mfma_f32_16x16x32_bf16 v[98:101], v[170:173], v[192:195], v[98:101]
	v_mfma_f32_16x16x32_bf16 v[90:93], v[160:163], v[200:203], v[90:93]
	v_mfma_f32_16x16x32_bf16 v[82:85], v[170:173], v[200:203], v[82:85]
	v_mfma_f32_16x16x32_bf16 v[74:77], v[160:163], v[208:211], v[74:77]
	v_mfma_f32_16x16x32_bf16 v[66:69], v[170:173], v[208:211], v[66:69]
	s_setprio 0
	s_barrier
	s_add_i32 s64, s64, s23
	s_mov_b32 m0, s64
	ds_read_b128 v[176:179], v186 offset:16384
	ds_read_b128 v[182:185], v186 offset:17408
	ds_read_b128 v[188:191], v186 offset:18432
	ds_read_b128 v[192:195], v186 offset:19456
	ds_read_b128 v[196:199], v186 offset:20480
	ds_read_b128 v[200:203], v186 offset:21504
	ds_read_b128 v[204:207], v186 offset:22528
	ds_read_b128 v[208:211], v186 offset:23552
	global_load_lds_dwordx4 v0, s[46:47]
	s_add_i32 m0, s64, 0x2000
	s_add_u32 s64, s46, 0x40000
	s_addc_u32 s65, s47, 0
	s_add_i32 s68, s68, s23
	global_load_lds_dwordx4 v146, s[46:47]
	s_mov_b32 m0, s68
	s_nop 0
	global_load_lds_dwordx4 v0, s[64:65]
	s_add_i32 m0, s68, 0x2000
	s_nop 0
	global_load_lds_dwordx4 v146, s[64:65]
	s_mov_b32 m0, s51
	s_nop 0
	global_load_lds_dwordx4 v150, s[48:49]
	s_mov_b32 m0, s52
	s_nop 0
	global_load_lds_dwordx4 v148, s[48:49]
	s_waitcnt vmcnt(8)
	s_waitcnt lgkmcnt(0)
	s_barrier
	s_setprio 1
	v_mfma_f32_16x16x32_bf16 v[62:65], v[130:133], v[176:179], v[62:65]
	v_mfma_f32_16x16x32_bf16 v[54:57], v[138:141], v[176:179], v[54:57]
	v_mfma_f32_16x16x32_bf16 v[46:49], v[130:133], v[188:191], v[46:49]
	v_mfma_f32_16x16x32_bf16 v[38:41], v[138:141], v[188:191], v[38:41]
	v_mfma_f32_16x16x32_bf16 v[30:33], v[130:133], v[196:199], v[30:33]
	v_mfma_f32_16x16x32_bf16 v[22:25], v[138:141], v[196:199], v[22:25]
	v_mfma_f32_16x16x32_bf16 v[14:17], v[130:133], v[204:207], v[14:17]
	v_mfma_f32_16x16x32_bf16 v[6:9], v[138:141], v[204:207], v[6:9]
	v_mfma_f32_16x16x32_bf16 v[62:65], v[134:137], v[182:185], v[62:65]
	v_mfma_f32_16x16x32_bf16 v[54:57], v[142:145], v[182:185], v[54:57]
	v_mfma_f32_16x16x32_bf16 v[46:49], v[134:137], v[192:195], v[46:49]
	v_mfma_f32_16x16x32_bf16 v[38:41], v[142:145], v[192:195], v[38:41]
	v_mfma_f32_16x16x32_bf16 v[30:33], v[134:137], v[200:203], v[30:33]
	v_mfma_f32_16x16x32_bf16 v[22:25], v[142:145], v[200:203], v[22:25]
	v_mfma_f32_16x16x32_bf16 v[14:17], v[134:137], v[208:211], v[14:17]
	v_mfma_f32_16x16x32_bf16 v[6:9], v[142:145], v[208:211], v[6:9]
	v_mfma_f32_16x16x32_bf16 v[58:61], v[156:159], v[176:179], v[58:61]
	v_mfma_f32_16x16x32_bf16 v[50:53], v[164:167], v[176:179], v[50:53]
	v_mfma_f32_16x16x32_bf16 v[42:45], v[156:159], v[188:191], v[42:45]
	v_mfma_f32_16x16x32_bf16 v[34:37], v[164:167], v[188:191], v[34:37]
	v_mfma_f32_16x16x32_bf16 v[26:29], v[156:159], v[196:199], v[26:29]
	v_mfma_f32_16x16x32_bf16 v[18:21], v[164:167], v[196:199], v[18:21]
	v_mfma_f32_16x16x32_bf16 v[10:13], v[156:159], v[204:207], v[10:13]
	v_mfma_f32_16x16x32_bf16 v[2:5], v[164:167], v[204:207], v[2:5]
	v_mfma_f32_16x16x32_bf16 v[58:61], v[160:163], v[182:185], v[58:61]
	v_mfma_f32_16x16x32_bf16 v[50:53], v[170:173], v[182:185], v[50:53]
	v_mfma_f32_16x16x32_bf16 v[42:45], v[160:163], v[192:195], v[42:45]
	v_mfma_f32_16x16x32_bf16 v[34:37], v[170:173], v[192:195], v[34:37]
	v_mfma_f32_16x16x32_bf16 v[26:29], v[160:163], v[200:203], v[26:29]
	v_mfma_f32_16x16x32_bf16 v[18:21], v[170:173], v[200:203], v[18:21]
	v_mfma_f32_16x16x32_bf16 v[10:13], v[160:163], v[208:211], v[10:13]
	v_mfma_f32_16x16x32_bf16 v[2:5], v[170:173], v[208:211], v[2:5]
	s_setprio 0
	s_barrier
; #define PG8_STAGE(bufoff, gbase, voff) do { _Pragma("unroll") for (int _i = 0; _i < 2; ++_i) \
;         __builtin_amdgcn_global_load_lds((const unsigned*)((const char*)(gbase) + (voff)[_i]), (PG8_LAS unsigned*)(lds + (bufoff) + ldsw + _i * 8192), 16, 0, 0); } while (0)
; #define PG8_LDA(dst, b, h) do { _Pragma("unroll") for (int m = 0; m < 4; ++m) _Pragma("unroll") for (int k = 0; k < 2; ++k) dst[m][k] = *(const PG8_LAS bf16x8*)(lds + PG8_SA(b, h) + aoff + m * 2048 + k * 1024); } while (0)
; #define PG8_LDB(dst, b, h) do { _Pragma("unroll") for (int n = 0; n < 2; ++n) _Pragma("unroll") for (int k = 0; k < 2; ++k) dst[n][k] = *(const PG8_LAS bf16x8*)(lds + PG8_SB(b, h) + boff + n * 2048 + k * 1024); } while (0)
; #define PG8_MMA(ai, bj, At, Bt) do { __builtin_amdgcn_s_setprio(1); _Pragma("unroll") for (int m = 0; m < 4; ++m) _Pragma("unroll") for (int n = 0; n < 2; ++n) _Pragma("unroll") for (int k = 0; k < 2; ++k) \
;         acc[ai][bj][m][n] = __builtin_amdgcn_mfma_f32_16x16x32_bf16(Bt[n][k], At[m][k], acc[ai][bj][m][n], 0, 0, 0); __builtin_amdgcn_s_setprio(0); } while (0)
; #define PG8_WAIT_V(n) asm volatile("s_waitcnt vmcnt(" #n ")" ::: "memory")
; #define PG8_WAIT_L(n) asm volatile("s_waitcnt lgkmcnt(" #n ")" ::: "memory")
; #define PG8_BAR __builtin_amdgcn_s_barrier()
; #define PG8_SCHED __builtin_amdgcn_sched_barrier(0)
; template <class Epi, class Sched, bool ALIGN_EPI = false, bool SP2 = false, bool SPLITK = false>
; __device__ __forceinline__ void gemm_phase(PG8_LAS unsigned char* lds, const Gemm g, const Sched& S, const Epi& E) {
;     ...
;             PG8_LDB(B0, 1, 0); PG8_LDB(B1, 1, 1); PG8_SCHED; PG8_LDA(At, 1, 0); PG8_STAGE(PG8_SA(0, 1), a2 + hstep, voffA);
;             PG8_WAIT_V(8); PG8_WAIT_L(0); PG8_BAR; PG8_MMA(0, 0, At, B0); PG8_MMA(0, 1, At, B1); PG8_BAR; PG8_SCHED;
;             PG8_LDA(At, 1, 1); PG8_STAGE(PG8_SB(1, 0), b3, voffB); PG8_STAGE(PG8_SB(1, 1), b3 + hstep, voffB); PG8_STAGE(PG8_SA(1, 0), a3, voffA);
;             PG8_WAIT_V(8); PG8_WAIT_L(0); PG8_BAR; PG8_MMA(1, 0, At, B0); PG8_MMA(1, 1, At, B1); PG8_BAR; PG8_SCHED;
;     ...
;         if constexpr (ALIGN_EPI) { if (wr == 0) PG8_BAR; }
	s_add_i32 s64, 0, 0x18000
	s_add_i32 s65, 0, 0x1c000
	v_add_u32_e32 v142, s64, v181
	v_add_u32_e32 v168, s65, v181
	ds_read_b128 v[130:133], v142
	ds_read_b128 v[134:137], v142 offset:1024
	ds_read_b128 v[138:141], v142 offset:2048
	ds_read_b128 v[142:145], v142 offset:3072
	ds_read_b128 v[156:159], v168
	ds_read_b128 v[160:163], v168 offset:1024
	ds_read_b128 v[164:167], v168 offset:2048
	ds_read_b128 v[170:173], v168 offset:3072
	s_add_u32 vcc_lo, s48, 0x80
	s_addc_u32 vcc_hi, s49, 0
	s_add_u32 s48, s48, 0x40000
	s_addc_u32 s49, s49, 0
	s_mov_b32 m0, s53
	ds_read_b128 v[176:179], v186 offset:32768
	ds_read_b128 v[182:185], v186 offset:33792
	ds_read_b128 v[188:191], v186 offset:34816
	ds_read_b128 v[192:195], v186 offset:35840
	ds_read_b128 v[196:199], v186 offset:36864
	ds_read_b128 v[200:203], v186 offset:37888
	ds_read_b128 v[204:207], v186 offset:38912
	ds_read_b128 v[208:211], v186 offset:39936
	global_load_lds_dwordx4 v150, s[48:49]
	s_mov_b32 m0, s54
	s_nop 0
	global_load_lds_dwordx4 v148, s[48:49]
	s_waitcnt vmcnt(8)
	s_waitcnt lgkmcnt(0)
	s_barrier
	s_setprio 1
	v_mfma_f32_16x16x32_bf16 v[126:129], v[130:133], v[176:179], v[126:129]
	v_mfma_f32_16x16x32_bf16 v[118:121], v[138:141], v[176:179], v[118:121]
	v_mfma_f32_16x16x32_bf16 v[110:113], v[130:133], v[188:191], v[110:113]
	v_mfma_f32_16x16x32_bf16 v[102:105], v[138:141], v[188:191], v[102:105]
	v_mfma_f32_16x16x32_bf16 v[94:97], v[130:133], v[196:199], v[94:97]
	v_mfma_f32_16x16x32_bf16 v[86:89], v[138:141], v[196:199], v[86:89]
	v_mfma_f32_16x16x32_bf16 v[78:81], v[130:133], v[204:207], v[78:81]
	v_mfma_f32_16x16x32_bf16 v[70:73], v[138:141], v[204:207], v[70:73]
	v_mfma_f32_16x16x32_bf16 v[126:129], v[134:137], v[182:185], v[126:129]
	v_mfma_f32_16x16x32_bf16 v[118:121], v[142:145], v[182:185], v[118:121]
	v_mfma_f32_16x16x32_bf16 v[110:113], v[134:137], v[192:195], v[110:113]
	v_mfma_f32_16x16x32_bf16 v[102:105], v[142:145], v[192:195], v[102:105]
	v_mfma_f32_16x16x32_bf16 v[94:97], v[134:137], v[200:203], v[94:97]
	v_mfma_f32_16x16x32_bf16 v[86:89], v[142:145], v[200:203], v[86:89]
	v_mfma_f32_16x16x32_bf16 v[78:81], v[134:137], v[208:211], v[78:81]
	v_mfma_f32_16x16x32_bf16 v[70:73], v[142:145], v[208:211], v[70:73]
	v_mfma_f32_16x16x32_bf16 v[122:125], v[156:159], v[176:179], v[122:125]
	v_mfma_f32_16x16x32_bf16 v[114:117], v[164:167], v[176:179], v[114:117]
	v_mfma_f32_16x16x32_bf16 v[106:109], v[156:159], v[188:191], v[106:109]
	v_mfma_f32_16x16x32_bf16 v[98:101], v[164:167], v[188:191], v[98:101]
	v_mfma_f32_16x16x32_bf16 v[90:93], v[156:159], v[196:199], v[90:93]
	v_mfma_f32_16x16x32_bf16 v[82:85], v[164:167], v[196:199], v[82:85]
	v_mfma_f32_16x16x32_bf16 v[74:77], v[156:159], v[204:207], v[74:77]
	v_mfma_f32_16x16x32_bf16 v[66:69], v[164:167], v[204:207], v[66:69]
	v_mfma_f32_16x16x32_bf16 v[122:125], v[160:163], v[182:185], v[122:125]
	v_mfma_f32_16x16x32_bf16 v[114:117], v[170:173], v[182:185], v[114:117]
	v_mfma_f32_16x16x32_bf16 v[106:109], v[160:163], v[192:195], v[106:109]
	v_mfma_f32_16x16x32_bf16 v[98:101], v[170:173], v[192:195], v[98:101]
	v_mfma_f32_16x16x32_bf16 v[90:93], v[160:163], v[200:203], v[90:93]
	v_mfma_f32_16x16x32_bf16 v[82:85], v[170:173], v[200:203], v[82:85]
	v_mfma_f32_16x16x32_bf16 v[74:77], v[160:163], v[208:211], v[74:77]
	v_mfma_f32_16x16x32_bf16 v[66:69], v[170:173], v[208:211], v[66:69]
	s_setprio 0
	s_barrier
	s_add_i32 s48, s64, s23
	s_add_u32 s46, s46, 0x80
	s_addc_u32 s47, s47, 0
	s_mov_b32 m0, s48
	ds_read_b128 v[176:179], v186 offset:49152
	ds_read_b128 v[182:185], v186 offset:50176
	ds_read_b128 v[188:191], v186 offset:51200
	ds_read_b128 v[192:195], v186 offset:52224
	ds_read_b128 v[196:199], v186 offset:53248
	ds_read_b128 v[200:203], v186 offset:54272
	ds_read_b128 v[204:207], v186 offset:55296
	ds_read_b128 v[208:211], v186 offset:56320
	global_load_lds_dwordx4 v0, s[46:47]
	s_add_i32 m0, s48, 0x2000
	s_add_i32 s48, s65, s23
	global_load_lds_dwordx4 v146, s[46:47]
	s_add_u32 s46, s46, 0x40000
	s_addc_u32 s47, s47, 0
	s_mov_b32 m0, s48
	s_nop 0
	global_load_lds_dwordx4 v0, s[46:47]
	s_add_i32 m0, s48, 0x2000
	s_nop 0
	global_load_lds_dwordx4 v146, s[46:47]
	s_mov_b32 m0, s55
	s_nop 0
	global_load_lds_dwordx4 v150, vcc
	s_mov_b32 m0, s56
	s_nop 0
	global_load_lds_dwordx4 v148, vcc
	s_waitcnt vmcnt(8)
	s_waitcnt lgkmcnt(0)
	s_barrier
	s_setprio 1
	v_mfma_f32_16x16x32_bf16 v[62:65], v[130:133], v[176:179], v[62:65]
	v_mfma_f32_16x16x32_bf16 v[54:57], v[138:141], v[176:179], v[54:57]
	v_mfma_f32_16x16x32_bf16 v[46:49], v[130:133], v[188:191], v[46:49]
	v_mfma_f32_16x16x32_bf16 v[38:41], v[138:141], v[188:191], v[38:41]
	v_mfma_f32_16x16x32_bf16 v[30:33], v[130:133], v[196:199], v[30:33]
	v_mfma_f32_16x16x32_bf16 v[22:25], v[138:141], v[196:199], v[22:25]
	v_mfma_f32_16x16x32_bf16 v[14:17], v[130:133], v[204:207], v[14:17]
	v_mfma_f32_16x16x32_bf16 v[6:9], v[138:141], v[204:207], v[6:9]
	v_mfma_f32_16x16x32_bf16 v[62:65], v[134:137], v[182:185], v[62:65]
	v_mfma_f32_16x16x32_bf16 v[54:57], v[142:145], v[182:185], v[54:57]
	v_mfma_f32_16x16x32_bf16 v[46:49], v[134:137], v[192:195], v[46:49]
	v_mfma_f32_16x16x32_bf16 v[38:41], v[142:145], v[192:195], v[38:41]
	v_mfma_f32_16x16x32_bf16 v[30:33], v[134:137], v[200:203], v[30:33]
	v_mfma_f32_16x16x32_bf16 v[22:25], v[142:145], v[200:203], v[22:25]
	v_mfma_f32_16x16x32_bf16 v[14:17], v[134:137], v[208:211], v[14:17]
	v_mfma_f32_16x16x32_bf16 v[6:9], v[142:145], v[208:211], v[6:9]
	v_mfma_f32_16x16x32_bf16 v[58:61], v[156:159], v[176:179], v[58:61]
	v_mfma_f32_16x16x32_bf16 v[50:53], v[164:167], v[176:179], v[50:53]
	v_mfma_f32_16x16x32_bf16 v[42:45], v[156:159], v[188:191], v[42:45]
	v_mfma_f32_16x16x32_bf16 v[34:37], v[164:167], v[188:191], v[34:37]
	v_mfma_f32_16x16x32_bf16 v[26:29], v[156:159], v[196:199], v[26:29]
	v_mfma_f32_16x16x32_bf16 v[18:21], v[164:167], v[196:199], v[18:21]
	v_mfma_f32_16x16x32_bf16 v[10:13], v[156:159], v[204:207], v[10:13]
	v_mfma_f32_16x16x32_bf16 v[2:5], v[164:167], v[204:207], v[2:5]
	v_mfma_f32_16x16x32_bf16 v[58:61], v[160:163], v[182:185], v[58:61]
	v_mfma_f32_16x16x32_bf16 v[50:53], v[170:173], v[182:185], v[50:53]
	v_mfma_f32_16x16x32_bf16 v[42:45], v[160:163], v[192:195], v[42:45]
	v_mfma_f32_16x16x32_bf16 v[34:37], v[170:173], v[192:195], v[34:37]
	v_mfma_f32_16x16x32_bf16 v[26:29], v[160:163], v[200:203], v[26:29]
	v_mfma_f32_16x16x32_bf16 v[18:21], v[170:173], v[200:203], v[18:21]
	v_mfma_f32_16x16x32_bf16 v[10:13], v[160:163], v[208:211], v[10:13]
	v_mfma_f32_16x16x32_bf16 v[2:5], v[170:173], v[208:211], v[2:5]
	s_setprio 0
	s_barrier
	s_add_i32 s45, s45, 2
	s_add_u32 s42, s42, 0x100
	s_addc_u32 s43, s43, 0
	s_add_u32 s25, s25, 0x100
	s_addc_u32 s41, s41, 0
	s_cmp_gt_u32 s45, 13
	s_cbranch_scc0 .LBB0_582
	s_and_b64 vcc, exec, s[16:17]
	s_cbranch_vccz .LBB0_585
	s_barrier

; #define PG8_STAGE(bufoff, gbase, voff) do { _Pragma("unroll") for (int _i = 0; _i < 2; ++_i) \
;         __builtin_amdgcn_global_load_lds((const unsigned*)((const char*)(gbase) + (voff)[_i]), (PG8_LAS unsigned*)(lds + (bufoff) + ldsw + _i * 8192), 16, 0, 0); } while (0)
; #define PG8_LDA(dst, b, h) do { _Pragma("unroll") for (int m = 0; m < 4; ++m) _Pragma("unroll") for (int k = 0; k < 2; ++k) dst[m][k] = *(const PG8_LAS bf16x8*)(lds + PG8_SA(b, h) + aoff + m * 2048 + k * 1024); } while (0)
; #define PG8_LDB(dst, b, h) do { _Pragma("unroll") for (int n = 0; n < 2; ++n) _Pragma("unroll") for (int k = 0; k < 2; ++k) dst[n][k] = *(const PG8_LAS bf16x8*)(lds + PG8_SB(b, h) + boff + n * 2048 + k * 1024); } while (0)
; #define PG8_MMA(ai, bj, At, Bt) do { __builtin_amdgcn_s_setprio(1); _Pragma("unroll") for (int m = 0; m < 4; ++m) _Pragma("unroll") for (int n = 0; n < 2; ++n) _Pragma("unroll") for (int k = 0; k < 2; ++k) \
;         acc[ai][bj][m][n] = __builtin_amdgcn_mfma_f32_16x16x32_bf16(Bt[n][k], At[m][k], acc[ai][bj][m][n], 0, 0, 0); __builtin_amdgcn_s_setprio(0); } while (0)
; #define PG8_WAIT_V(n) asm volatile("s_waitcnt vmcnt(" #n ")" ::: "memory")
; #define PG8_WAIT_L(n) asm volatile("s_waitcnt lgkmcnt(" #n ")" ::: "memory")
; #define PG8_BAR __builtin_amdgcn_s_barrier()
; #define PG8_SCHED __builtin_amdgcn_sched_barrier(0)
; template <class Epi, class Sched, bool ALIGN_EPI = false, bool SP2 = false, bool SPLITK = false>
; __device__ __forceinline__ void gemm_phase(PG8_LAS unsigned char* lds, const Gemm g, const Sched& S, const Epi& E) {
;     ...
;             const char* a1 = PG8_TA(t + 1);
;             const char* a2 = last ? nA : PG8_TA(t + 2); const char* b2 = last ? nB : PG8_TB(t + 2);
;             const char* a3 = a2 + kstep; const char* b3 = b2 + kstep;
;             if (last && has_next) S.a_ready(nxt);
;             if constexpr (SP2) {
;             PG8_LDB(B0, 0, 0); PG8_LDB(B1, 0, 1); PG8_SCHED; PG8_LDA(At, 0, 0); PG8_STAGE(PG8_SA(1, 1), a1 + hstep, voffA);
;             PG8_WAIT_V(8); PG8_WAIT_L(0); PG8_BAR; PG8_MMA(0, 0, At, B0); PG8_MMA(0, 1, At, B1); PG8_BAR; PG8_SCHED;
;             PG8_LDA(At, 0, 1); PG8_STAGE(PG8_SB(0, 0), b2, voffB); PG8_STAGE(PG8_SB(0, 1), b2 + hstep, voffB); PG8_STAGE(PG8_SA(0, 0), a2, voffA);
;             PG8_WAIT_V(8); PG8_WAIT_L(0); PG8_BAR; PG8_MMA(1, 0, At, B0); PG8_MMA(1, 1, At, B1); PG8_BAR; PG8_SCHED;
.LBB0_701:
	s_add_u32 s40, s42, 0x100
	s_addc_u32 s41, s43, 0
	s_add_i32 s58, 0, 0x10000
	s_cmp_eq_u32 s57, 40
	s_cselect_b32 s49, s35, s41
	s_cselect_b32 s48, s34, s40
	s_cselect_b32 s47, s37, s45
	s_cselect_b32 s46, s36, s12
	s_add_i32 s59, 0, 0x14000
	v_add_u32_e32 v118, s58, v224
	v_add_u32_e32 v150, s59, v224
	ds_read_b128 v[82:85], v118
	ds_read_b128 v[94:97], v118 offset:1024
	ds_read_b128 v[106:109], v118 offset:2048
	ds_read_b128 v[118:121], v118 offset:3072
	ds_read_b128 v[130:133], v150
	ds_read_b128 v[142:145], v150 offset:1024
	ds_read_b128 v[146:149], v150 offset:2048
	ds_read_b128 v[150:153], v150 offset:3072
	s_add_i32 m0, s24, 0xc000
	ds_read_b128 v[162:165], v225
	ds_read_b128 v[166:169], v225 offset:1024
	ds_read_b128 v[170:173], v225 offset:2048
	ds_read_b128 v[174:177], v225 offset:3072
	ds_read_b128 v[178:181], v225 offset:4096
	ds_read_b128 v[182:185], v225 offset:5120
	ds_read_b128 v[186:189], v225 offset:6144
	ds_read_b128 v[190:193], v225 offset:7168
	global_load_lds_dwordx4 v200, s[42:43]
	s_add_i32 m0, s24, 0xe000
	s_nop 0
	global_load_lds_dwordx4 v202, s[42:43]
	s_waitcnt vmcnt(8)
	s_waitcnt lgkmcnt(0)
	s_barrier
	s_setprio 1
	v_mfma_f32_16x16x32_bf16 v[158:161], v[82:85], v[162:165], v[158:161]
	v_mfma_f32_16x16x32_bf16 v[154:157], v[106:109], v[162:165], v[154:157]
	v_mfma_f32_16x16x32_bf16 v[126:129], v[82:85], v[170:173], v[126:129]
	v_mfma_f32_16x16x32_bf16 v[122:125], v[106:109], v[170:173], v[122:125]
	v_mfma_f32_16x16x32_bf16 v[102:105], v[82:85], v[178:181], v[102:105]
	v_mfma_f32_16x16x32_bf16 v[98:101], v[106:109], v[178:181], v[98:101]
	v_mfma_f32_16x16x32_bf16 v[78:81], v[82:85], v[186:189], v[78:81]
	v_mfma_f32_16x16x32_bf16 v[74:77], v[106:109], v[186:189], v[74:77]
	v_mfma_f32_16x16x32_bf16 v[158:161], v[94:97], v[166:169], v[158:161]
	v_mfma_f32_16x16x32_bf16 v[154:157], v[118:121], v[166:169], v[154:157]
	v_mfma_f32_16x16x32_bf16 v[126:129], v[94:97], v[174:177], v[126:129]
	v_mfma_f32_16x16x32_bf16 v[122:125], v[118:121], v[174:177], v[122:125]
	v_mfma_f32_16x16x32_bf16 v[102:105], v[94:97], v[182:185], v[102:105]
	v_mfma_f32_16x16x32_bf16 v[98:101], v[118:121], v[182:185], v[98:101]
	v_mfma_f32_16x16x32_bf16 v[78:81], v[94:97], v[190:193], v[78:81]
	v_mfma_f32_16x16x32_bf16 v[74:77], v[118:121], v[190:193], v[74:77]
	v_mfma_f32_16x16x32_bf16 v[138:141], v[130:133], v[162:165], v[138:141]
	v_mfma_f32_16x16x32_bf16 v[134:137], v[146:149], v[162:165], v[134:137]
	v_mfma_f32_16x16x32_bf16 v[114:117], v[130:133], v[170:173], v[114:117]
	v_mfma_f32_16x16x32_bf16 v[110:113], v[146:149], v[170:173], v[110:113]
	v_mfma_f32_16x16x32_bf16 v[90:93], v[130:133], v[178:181], v[90:93]
	v_mfma_f32_16x16x32_bf16 v[86:89], v[146:149], v[178:181], v[86:89]
	v_mfma_f32_16x16x32_bf16 v[70:73], v[130:133], v[186:189], v[70:73]
	v_mfma_f32_16x16x32_bf16 v[66:69], v[146:149], v[186:189], v[66:69]
	v_mfma_f32_16x16x32_bf16 v[138:141], v[142:145], v[166:169], v[138:141]
	v_mfma_f32_16x16x32_bf16 v[134:137], v[150:153], v[166:169], v[134:137]
	v_mfma_f32_16x16x32_bf16 v[114:117], v[142:145], v[174:177], v[114:117]
	v_mfma_f32_16x16x32_bf16 v[110:113], v[150:153], v[174:177], v[110:113]
	v_mfma_f32_16x16x32_bf16 v[90:93], v[142:145], v[182:185], v[90:93]
	v_mfma_f32_16x16x32_bf16 v[86:89], v[150:153], v[182:185], v[86:89]
	v_mfma_f32_16x16x32_bf16 v[70:73], v[142:145], v[190:193], v[70:73]
	v_mfma_f32_16x16x32_bf16 v[66:69], v[150:153], v[190:193], v[66:69]
	s_setprio 0
	s_barrier
	s_add_i32 s42, s58, s23
	s_mov_b32 m0, s42
	ds_read_b128 v[162:165], v225 offset:16384
	ds_read_b128 v[166:169], v225 offset:17408
	ds_read_b128 v[170:173], v225 offset:18432
	ds_read_b128 v[174:177], v225 offset:19456
	ds_read_b128 v[178:181], v225 offset:20480
	ds_read_b128 v[182:185], v225 offset:21504
	ds_read_b128 v[186:189], v225 offset:22528
	ds_read_b128 v[190:193], v225 offset:23552
	global_load_lds_dwordx4 v0, s[46:47]
	s_add_i32 m0, s42, 0x2000
	s_add_u32 s42, s46, 0xb0000
	s_addc_u32 s43, s47, 0
	s_add_i32 s58, s59, s23
	global_load_lds_dwordx4 v198, s[46:47]
	s_mov_b32 m0, s58
	s_nop 0
	global_load_lds_dwordx4 v0, s[42:43]
	s_add_i32 m0, s58, 0x2000
	s_nop 0
	global_load_lds_dwordx4 v198, s[42:43]
	s_mov_b32 m0, s24
	s_nop 0
	global_load_lds_dwordx4 v194, s[48:49]
	s_mov_b32 m0, s25
	s_nop 0
	global_load_lds_dwordx4 v196, s[48:49]
	s_waitcnt vmcnt(8)
	s_waitcnt lgkmcnt(0)
	s_barrier
	s_setprio 1
	v_mfma_f32_16x16x32_bf16 v[62:65], v[82:85], v[162:165], v[62:65]
	v_mfma_f32_16x16x32_bf16 v[58:61], v[106:109], v[162:165], v[58:61]
	v_mfma_f32_16x16x32_bf16 v[46:49], v[82:85], v[170:173], v[46:49]
	v_mfma_f32_16x16x32_bf16 v[42:45], v[106:109], v[170:173], v[42:45]
	v_mfma_f32_16x16x32_bf16 v[30:33], v[82:85], v[178:181], v[30:33]
	v_mfma_f32_16x16x32_bf16 v[26:29], v[106:109], v[178:181], v[26:29]
	v_mfma_f32_16x16x32_bf16 v[14:17], v[82:85], v[186:189], v[14:17]
	v_mfma_f32_16x16x32_bf16 v[10:13], v[106:109], v[186:189], v[10:13]
	v_mfma_f32_16x16x32_bf16 v[62:65], v[94:97], v[166:169], v[62:65]
	v_mfma_f32_16x16x32_bf16 v[58:61], v[118:121], v[166:169], v[58:61]
	v_mfma_f32_16x16x32_bf16 v[46:49], v[94:97], v[174:177], v[46:49]
	v_mfma_f32_16x16x32_bf16 v[42:45], v[118:121], v[174:177], v[42:45]
	v_mfma_f32_16x16x32_bf16 v[30:33], v[94:97], v[182:185], v[30:33]
	v_mfma_f32_16x16x32_bf16 v[26:29], v[118:121], v[182:185], v[26:29]
	v_mfma_f32_16x16x32_bf16 v[14:17], v[94:97], v[190:193], v[14:17]
	v_mfma_f32_16x16x32_bf16 v[10:13], v[118:121], v[190:193], v[10:13]
	v_mfma_f32_16x16x32_bf16 v[54:57], v[130:133], v[162:165], v[54:57]
	v_mfma_f32_16x16x32_bf16 v[50:53], v[146:149], v[162:165], v[50:53]
	v_mfma_f32_16x16x32_bf16 v[38:41], v[130:133], v[170:173], v[38:41]
	v_mfma_f32_16x16x32_bf16 v[34:37], v[146:149], v[170:173], v[34:37]
	v_mfma_f32_16x16x32_bf16 v[22:25], v[130:133], v[178:181], v[22:25]
	v_mfma_f32_16x16x32_bf16 v[18:21], v[146:149], v[178:181], v[18:21]
	v_mfma_f32_16x16x32_bf16 v[6:9], v[130:133], v[186:189], v[6:9]
	v_mfma_f32_16x16x32_bf16 v[2:5], v[146:149], v[186:189], v[2:5]
	v_mfma_f32_16x16x32_bf16 v[54:57], v[142:145], v[166:169], v[54:57]
	v_mfma_f32_16x16x32_bf16 v[50:53], v[150:153], v[166:169], v[50:53]
	v_mfma_f32_16x16x32_bf16 v[38:41], v[142:145], v[174:177], v[38:41]
	v_mfma_f32_16x16x32_bf16 v[34:37], v[150:153], v[174:177], v[34:37]
	v_mfma_f32_16x16x32_bf16 v[22:25], v[142:145], v[182:185], v[22:25]
	v_mfma_f32_16x16x32_bf16 v[18:21], v[150:153], v[182:185], v[18:21]
	v_mfma_f32_16x16x32_bf16 v[6:9], v[142:145], v[190:193], v[6:9]
	v_mfma_f32_16x16x32_bf16 v[2:5], v[150:153], v[190:193], v[2:5]
	s_setprio 0
	s_barrier
; #define PG8_STAGE(bufoff, gbase, voff) do { _Pragma("unroll") for (int _i = 0; _i < 2; ++_i) \
;         __builtin_amdgcn_global_load_lds((const unsigned*)((const char*)(gbase) + (voff)[_i]), (PG8_LAS unsigned*)(lds + (bufoff) + ldsw + _i * 8192), 16, 0, 0); } while (0)
; #define PG8_LDA(dst, b, h) do { _Pragma("unroll") for (int m = 0; m < 4; ++m) _Pragma("unroll") for (int k = 0; k < 2; ++k) dst[m][k] = *(const PG8_LAS bf16x8*)(lds + PG8_SA(b, h) + aoff + m * 2048 + k * 1024); } while (0)
; #define PG8_LDB(dst, b, h) do { _Pragma("unroll") for (int n = 0; n < 2; ++n) _Pragma("unroll") for (int k = 0; k < 2; ++k) dst[n][k] = *(const PG8_LAS bf16x8*)(lds + PG8_SB(b, h) + boff + n * 2048 + k * 1024); } while (0)
; #define PG8_MMA(ai, bj, At, Bt) do { __builtin_amdgcn_s_setprio(1); _Pragma("unroll") for (int m = 0; m < 4; ++m) _Pragma("unroll") for (int n = 0; n < 2; ++n) _Pragma("unroll") for (int k = 0; k < 2; ++k) \
;         acc[ai][bj][m][n] = __builtin_amdgcn_mfma_f32_16x16x32_bf16(Bt[n][k], At[m][k], acc[ai][bj][m][n], 0, 0, 0); __builtin_amdgcn_s_setprio(0); } while (0)
; #define PG8_WAIT_V(n) asm volatile("s_waitcnt vmcnt(" #n ")" ::: "memory")
; #define PG8_WAIT_L(n) asm volatile("s_waitcnt lgkmcnt(" #n ")" ::: "memory")
; #define PG8_BAR __builtin_amdgcn_s_barrier()
; #define PG8_SCHED __builtin_amdgcn_sched_barrier(0)
; template <class Epi, class Sched, bool ALIGN_EPI = false, bool SP2 = false, bool SPLITK = false>
; __device__ __forceinline__ void gemm_phase(PG8_LAS unsigned char* lds, const Gemm g, const Sched& S, const Epi& E) {
;     ...
;             PG8_LDB(B0, 1, 0); PG8_LDB(B1, 1, 1); PG8_SCHED; PG8_LDA(At, 1, 0); PG8_STAGE(PG8_SA(0, 1), a2 + hstep, voffA);
;             PG8_WAIT_V(8); PG8_WAIT_L(0); PG8_BAR; PG8_MMA(0, 0, At, B0); PG8_MMA(0, 1, At, B1); PG8_BAR; PG8_SCHED;
;             PG8_LDA(At, 1, 1); PG8_STAGE(PG8_SB(1, 0), b3, voffB); PG8_STAGE(PG8_SB(1, 1), b3 + hstep, voffB); PG8_STAGE(PG8_SA(1, 0), a3, voffA);
;             PG8_WAIT_V(8); PG8_WAIT_L(0); PG8_BAR; PG8_MMA(1, 0, At, B0); PG8_MMA(1, 1, At, B1); PG8_BAR; PG8_SCHED;
;     ...
;         if constexpr (ALIGN_EPI) { if (wr == 0) PG8_BAR; }
	s_add_i32 s58, 0, 0x18000
	s_add_i32 s59, 0, 0x1c000
	v_add_u32_e32 v118, s58, v224
	v_add_u32_e32 v150, s59, v224
	ds_read_b128 v[82:85], v118
	ds_read_b128 v[94:97], v118 offset:1024
	ds_read_b128 v[106:109], v118 offset:2048
	ds_read_b128 v[118:121], v118 offset:3072
	ds_read_b128 v[130:133], v150
	ds_read_b128 v[142:145], v150 offset:1024
	ds_read_b128 v[146:149], v150 offset:2048
	ds_read_b128 v[150:153], v150 offset:3072
	s_add_u32 s42, s48, 0xb0000
	s_addc_u32 s43, s49, 0
	s_mov_b32 m0, s33
	ds_read_b128 v[162:165], v225 offset:32768
	ds_read_b128 v[166:169], v225 offset:33792
	ds_read_b128 v[170:173], v225 offset:34816
	ds_read_b128 v[174:177], v225 offset:35840
	ds_read_b128 v[178:181], v225 offset:36864
	ds_read_b128 v[182:185], v225 offset:37888
	ds_read_b128 v[186:189], v225 offset:38912
	ds_read_b128 v[190:193], v225 offset:39936
	global_load_lds_dwordx4 v194, s[42:43]
	s_mov_b32 m0, s50
	s_nop 0
	global_load_lds_dwordx4 v196, s[42:43]
	s_waitcnt vmcnt(8)
	s_waitcnt lgkmcnt(0)
	s_barrier
	s_setprio 1
	v_mfma_f32_16x16x32_bf16 v[158:161], v[82:85], v[162:165], v[158:161]
	v_mfma_f32_16x16x32_bf16 v[154:157], v[106:109], v[162:165], v[154:157]
	v_mfma_f32_16x16x32_bf16 v[126:129], v[82:85], v[170:173], v[126:129]
	v_mfma_f32_16x16x32_bf16 v[122:125], v[106:109], v[170:173], v[122:125]
	v_mfma_f32_16x16x32_bf16 v[102:105], v[82:85], v[178:181], v[102:105]
	v_mfma_f32_16x16x32_bf16 v[98:101], v[106:109], v[178:181], v[98:101]
	v_mfma_f32_16x16x32_bf16 v[78:81], v[82:85], v[186:189], v[78:81]
	v_mfma_f32_16x16x32_bf16 v[74:77], v[106:109], v[186:189], v[74:77]
	v_mfma_f32_16x16x32_bf16 v[158:161], v[94:97], v[166:169], v[158:161]
	v_mfma_f32_16x16x32_bf16 v[154:157], v[118:121], v[166:169], v[154:157]
	v_mfma_f32_16x16x32_bf16 v[126:129], v[94:97], v[174:177], v[126:129]
	v_mfma_f32_16x16x32_bf16 v[122:125], v[118:121], v[174:177], v[122:125]
	v_mfma_f32_16x16x32_bf16 v[102:105], v[94:97], v[182:185], v[102:105]
	v_mfma_f32_16x16x32_bf16 v[98:101], v[118:121], v[182:185], v[98:101]
	v_mfma_f32_16x16x32_bf16 v[78:81], v[94:97], v[190:193], v[78:81]
	v_mfma_f32_16x16x32_bf16 v[74:77], v[118:121], v[190:193], v[74:77]
	v_mfma_f32_16x16x32_bf16 v[138:141], v[130:133], v[162:165], v[138:141]
	v_mfma_f32_16x16x32_bf16 v[134:137], v[146:149], v[162:165], v[134:137]
	v_mfma_f32_16x16x32_bf16 v[114:117], v[130:133], v[170:173], v[114:117]
	v_mfma_f32_16x16x32_bf16 v[110:113], v[146:149], v[170:173], v[110:113]
	v_mfma_f32_16x16x32_bf16 v[90:93], v[130:133], v[178:181], v[90:93]
	v_mfma_f32_16x16x32_bf16 v[86:89], v[146:149], v[178:181], v[86:89]
	v_mfma_f32_16x16x32_bf16 v[70:73], v[130:133], v[186:189], v[70:73]
	v_mfma_f32_16x16x32_bf16 v[66:69], v[146:149], v[186:189], v[66:69]
	v_mfma_f32_16x16x32_bf16 v[138:141], v[142:145], v[166:169], v[138:141]
	v_mfma_f32_16x16x32_bf16 v[134:137], v[150:153], v[166:169], v[134:137]
	v_mfma_f32_16x16x32_bf16 v[114:117], v[142:145], v[174:177], v[114:117]
	v_mfma_f32_16x16x32_bf16 v[110:113], v[150:153], v[174:177], v[110:113]
	v_mfma_f32_16x16x32_bf16 v[90:93], v[142:145], v[182:185], v[90:93]
	v_mfma_f32_16x16x32_bf16 v[86:89], v[150:153], v[182:185], v[86:89]
	v_mfma_f32_16x16x32_bf16 v[70:73], v[142:145], v[190:193], v[70:73]
	v_mfma_f32_16x16x32_bf16 v[66:69], v[150:153], v[190:193], v[66:69]
	s_setprio 0
	s_barrier
	s_add_i32 s42, s58, s23
	s_add_u32 vcc_lo, s46, 0x80
	s_addc_u32 vcc_hi, s47, 0
	s_mov_b32 m0, s42
	ds_read_b128 v[162:165], v225 offset:49152
	ds_read_b128 v[166:169], v225 offset:50176
	ds_read_b128 v[170:173], v225 offset:51200
	ds_read_b128 v[174:177], v225 offset:52224
	ds_read_b128 v[178:181], v225 offset:53248
	ds_read_b128 v[182:185], v225 offset:54272
	ds_read_b128 v[186:189], v225 offset:55296
	ds_read_b128 v[190:193], v225 offset:56320
	global_load_lds_dwordx4 v0, vcc
	s_add_i32 m0, s42, 0x2000
	s_add_u32 s42, s46, 0xb0080
	s_addc_u32 s43, s47, 0
	s_add_i32 s46, s59, s23
	global_load_lds_dwordx4 v198, vcc
	s_mov_b32 m0, s46
	s_nop 0
	global_load_lds_dwordx4 v0, s[42:43]
	s_add_i32 m0, s46, 0x2000
	s_nop 0
	global_load_lds_dwordx4 v198, s[42:43]
	s_add_u32 vcc_lo, s48, 0x80
	s_addc_u32 vcc_hi, s49, 0
	s_mov_b32 m0, s51
	s_nop 0
	global_load_lds_dwordx4 v194, vcc
	s_mov_b32 m0, s52
	s_nop 0
	global_load_lds_dwordx4 v196, vcc
	s_waitcnt vmcnt(8)
	s_waitcnt lgkmcnt(0)
	s_barrier
	s_setprio 1
	v_mfma_f32_16x16x32_bf16 v[62:65], v[82:85], v[162:165], v[62:65]
	v_mfma_f32_16x16x32_bf16 v[58:61], v[106:109], v[162:165], v[58:61]
	v_mfma_f32_16x16x32_bf16 v[46:49], v[82:85], v[170:173], v[46:49]
	v_mfma_f32_16x16x32_bf16 v[42:45], v[106:109], v[170:173], v[42:45]
	v_mfma_f32_16x16x32_bf16 v[30:33], v[82:85], v[178:181], v[30:33]
	v_mfma_f32_16x16x32_bf16 v[26:29], v[106:109], v[178:181], v[26:29]
	v_mfma_f32_16x16x32_bf16 v[14:17], v[82:85], v[186:189], v[14:17]
	v_mfma_f32_16x16x32_bf16 v[10:13], v[106:109], v[186:189], v[10:13]
	v_mfma_f32_16x16x32_bf16 v[62:65], v[94:97], v[166:169], v[62:65]
	v_mfma_f32_16x16x32_bf16 v[58:61], v[118:121], v[166:169], v[58:61]
	v_mfma_f32_16x16x32_bf16 v[46:49], v[94:97], v[174:177], v[46:49]
	v_mfma_f32_16x16x32_bf16 v[42:45], v[118:121], v[174:177], v[42:45]
	v_mfma_f32_16x16x32_bf16 v[30:33], v[94:97], v[182:185], v[30:33]
	v_mfma_f32_16x16x32_bf16 v[26:29], v[118:121], v[182:185], v[26:29]
	v_mfma_f32_16x16x32_bf16 v[14:17], v[94:97], v[190:193], v[14:17]
	v_mfma_f32_16x16x32_bf16 v[10:13], v[118:121], v[190:193], v[10:13]
	v_mfma_f32_16x16x32_bf16 v[54:57], v[130:133], v[162:165], v[54:57]
	v_mfma_f32_16x16x32_bf16 v[50:53], v[146:149], v[162:165], v[50:53]
	v_mfma_f32_16x16x32_bf16 v[38:41], v[130:133], v[170:173], v[38:41]
	v_mfma_f32_16x16x32_bf16 v[34:37], v[146:149], v[170:173], v[34:37]
	v_mfma_f32_16x16x32_bf16 v[22:25], v[130:133], v[178:181], v[22:25]
	v_mfma_f32_16x16x32_bf16 v[18:21], v[146:149], v[178:181], v[18:21]
	v_mfma_f32_16x16x32_bf16 v[6:9], v[130:133], v[186:189], v[6:9]
	v_mfma_f32_16x16x32_bf16 v[2:5], v[146:149], v[186:189], v[2:5]
	v_mfma_f32_16x16x32_bf16 v[54:57], v[142:145], v[166:169], v[54:57]
	v_mfma_f32_16x16x32_bf16 v[50:53], v[150:153], v[166:169], v[50:53]
	v_mfma_f32_16x16x32_bf16 v[38:41], v[142:145], v[174:177], v[38:41]
	v_mfma_f32_16x16x32_bf16 v[34:37], v[150:153], v[174:177], v[34:37]
	v_mfma_f32_16x16x32_bf16 v[22:25], v[142:145], v[182:185], v[22:25]
	v_mfma_f32_16x16x32_bf16 v[18:21], v[150:153], v[182:185], v[18:21]
	v_mfma_f32_16x16x32_bf16 v[6:9], v[142:145], v[190:193], v[6:9]
	v_mfma_f32_16x16x32_bf16 v[2:5], v[150:153], v[190:193], v[2:5]
	s_setprio 0
	s_barrier
	s_add_i32 s57, s57, 2
	s_add_u32 s12, s12, 0x100
	s_addc_u32 s45, s45, 0
	s_cmp_gt_u32 s57, 41
	s_mov_b64 s[42:43], s[40:41]
	s_cbranch_scc0 .LBB0_701
	s_and_b64 vcc, exec, s[18:19]
	s_cbranch_vccz .LBB0_704
	s_barrier
